# loop-edge edit: the 8-state exit pad behind the early barrier's last MFMA moved off the K-loop back-edge path onto the exit path (7 loops)
# baseline (speedup 1.0000x reference)
.LBB0_170:
	ds_read_b128 v[128:131], v168
	ds_read_b128 v[132:135], v168 offset:1024
	ds_read_b128 v[136:139], v168 offset:2048
	ds_read_b128 v[140:143], v168 offset:3072
	ds_read_b128 v[152:155], v169
	ds_read_b128 v[156:159], v169 offset:1024
	ds_read_b128 v[160:163], v169 offset:2048
	ds_read_b128 v[172:175], v169 offset:3072
	s_add_u32 s2, s52, 0x10000
	s_addc_u32 s3, s53, 0
	s_cmp_eq_u32 s88, 60
	s_cselect_b32 s48, s82, s2
	s_cselect_b32 s49, s39, s3
	s_cselect_b32 s90, s83, s54
	s_cselect_b32 s91, s15, s55
	s_add_u32 s80, s48, 0x8000
	s_addc_u32 s81, s49, 0
	ds_read_b128 v[176:179], v170
	ds_read_b128 v[180:183], v170 offset:1024
	ds_read_b128 v[184:187], v170 offset:2048
	ds_read_b128 v[188:191], v170 offset:3072
	ds_read_b128 v[192:195], v170 offset:4096
	ds_read_b128 v[196:199], v170 offset:5120
	ds_read_b128 v[200:203], v170 offset:6144
	ds_read_b128 v[204:207], v170 offset:7168
	s_add_u32 s92, s52, 0xc000
	s_addc_u32 s93, s53, 0
	s_mov_b32 m0, s72
	s_nop 0
	global_load_lds_dwordx4 v166, s[92:93]
	s_add_u32 s52, s52, 0xe000
	s_addc_u32 s53, s53, 0
	s_mov_b32 m0, s75
	s_nop 0
	global_load_lds_dwordx4 v166, s[52:53]
	s_waitcnt vmcnt(8)
	s_waitcnt lgkmcnt(0)
	s_add_u32 s92, s90, 0x8000
	s_addc_u32 s93, s91, 0
	s_barrier
	s_setprio 1
	s_waitcnt lgkmcnt(7)
	s_waitcnt lgkmcnt(0)
	v_mfma_f32_16x16x32_bf16 v[112:115], v[128:131], v[176:179], v[112:115]
	v_mfma_f32_16x16x32_bf16 v[112:115], v[132:135], v[180:183], v[112:115]
	v_mfma_f32_16x16x32_bf16 v[96:99], v[128:131], v[184:187], v[96:99]
	v_mfma_f32_16x16x32_bf16 v[96:99], v[132:135], v[188:191], v[96:99]
	v_mfma_f32_16x16x32_bf16 v[80:83], v[128:131], v[192:195], v[80:83]
	v_mfma_f32_16x16x32_bf16 v[80:83], v[132:135], v[196:199], v[80:83]
	v_mfma_f32_16x16x32_bf16 v[60:63], v[128:131], v[200:203], v[60:63]
	v_mfma_f32_16x16x32_bf16 v[60:63], v[132:135], v[204:207], v[60:63]
	v_mfma_f32_16x16x32_bf16 v[72:75], v[136:139], v[200:203], v[72:75]
	v_mfma_f32_16x16x32_bf16 v[72:75], v[140:143], v[204:207], v[72:75]
	v_mfma_f32_16x16x32_bf16 v[88:91], v[136:139], v[192:195], v[88:91]
	v_mfma_f32_16x16x32_bf16 v[88:91], v[140:143], v[196:199], v[88:91]
	v_mfma_f32_16x16x32_bf16 v[104:107], v[136:139], v[184:187], v[104:107]
	v_mfma_f32_16x16x32_bf16 v[104:107], v[140:143], v[188:191], v[104:107]
	v_mfma_f32_16x16x32_bf16 v[120:123], v[136:139], v[176:179], v[120:123]
	v_mfma_f32_16x16x32_bf16 v[120:123], v[140:143], v[180:183], v[120:123]
	s_setprio 0
	s_setprio 1
	s_waitcnt lgkmcnt(0)
	v_mfma_f32_16x16x32_bf16 v[116:119], v[152:155], v[176:179], v[116:119]
	v_mfma_f32_16x16x32_bf16 v[116:119], v[156:159], v[180:183], v[116:119]
	v_mfma_f32_16x16x32_bf16 v[100:103], v[152:155], v[184:187], v[100:103]
	v_mfma_f32_16x16x32_bf16 v[100:103], v[156:159], v[188:191], v[100:103]
	v_mfma_f32_16x16x32_bf16 v[84:87], v[152:155], v[192:195], v[84:87]
	v_mfma_f32_16x16x32_bf16 v[84:87], v[156:159], v[196:199], v[84:87]
	v_mfma_f32_16x16x32_bf16 v[68:71], v[152:155], v[200:203], v[68:71]
	v_mfma_f32_16x16x32_bf16 v[68:71], v[156:159], v[204:207], v[68:71]
	v_mfma_f32_16x16x32_bf16 v[76:79], v[160:163], v[200:203], v[76:79]
	v_mfma_f32_16x16x32_bf16 v[76:79], v[172:175], v[204:207], v[76:79]
	v_mfma_f32_16x16x32_bf16 v[92:95], v[160:163], v[192:195], v[92:95]
	v_mfma_f32_16x16x32_bf16 v[92:95], v[172:175], v[196:199], v[92:95]
	v_mfma_f32_16x16x32_bf16 v[108:111], v[160:163], v[184:187], v[108:111]
	v_mfma_f32_16x16x32_bf16 v[108:111], v[172:175], v[188:191], v[108:111]
	v_mfma_f32_16x16x32_bf16 v[124:127], v[160:163], v[176:179], v[124:127]
	s_barrier
	v_mfma_f32_16x16x32_bf16 v[124:127], v[172:175], v[180:183], v[124:127]
	s_setprio 0
	s_add_u32 s52, s90, 0x2000
	ds_read_b128 v[176:179], v170 offset:16384
	ds_read_b128 v[180:183], v170 offset:17408
	ds_read_b128 v[184:187], v170 offset:18432
	ds_read_b128 v[188:191], v170 offset:19456
	ds_read_b128 v[192:195], v170 offset:20480
	ds_read_b128 v[196:199], v170 offset:21504
	ds_read_b128 v[200:203], v170 offset:22528
	ds_read_b128 v[204:207], v170 offset:23552
	s_mov_b32 m0, s45
	s_nop 0
	global_load_lds_dwordx4 v166, s[90:91]
	s_addc_u32 s53, s91, 0
	s_mov_b32 m0, s47
	s_nop 0
	global_load_lds_dwordx4 v166, s[52:53]
	s_add_u32 s52, s90, 0x4000
	s_addc_u32 s53, s91, 0
	s_mov_b32 m0, s58
	s_nop 0
	global_load_lds_dwordx4 v166, s[52:53]
	s_add_u32 s52, s90, 0x6000
	s_addc_u32 s53, s91, 0
	s_mov_b32 m0, s59
	s_nop 0
	global_load_lds_dwordx4 v166, s[52:53]
	s_add_u32 s52, s48, 0x2000
	s_mov_b32 m0, s57
	s_nop 0
	global_load_lds_dwordx4 v166, s[48:49]
	s_addc_u32 s53, s49, 0
	s_mov_b32 m0, s60
	s_nop 0
	global_load_lds_dwordx4 v166, s[52:53]
	s_waitcnt vmcnt(8)
	s_waitcnt lgkmcnt(0)
	s_barrier
	s_setprio 1
	s_waitcnt lgkmcnt(7)
	s_waitcnt lgkmcnt(0)
	v_mfma_f32_16x16x32_bf16 v[48:51], v[128:131], v[176:179], v[48:51]
	v_mfma_f32_16x16x32_bf16 v[48:51], v[132:135], v[180:183], v[48:51]
	v_mfma_f32_16x16x32_bf16 v[32:35], v[128:131], v[184:187], v[32:35]
	v_mfma_f32_16x16x32_bf16 v[32:35], v[132:135], v[188:191], v[32:35]
	v_mfma_f32_16x16x32_bf16 v[16:19], v[128:131], v[192:195], v[16:19]
	v_mfma_f32_16x16x32_bf16 v[16:19], v[132:135], v[196:199], v[16:19]
	v_mfma_f32_16x16x32_bf16 v[0:3], v[128:131], v[200:203], v[0:3]
	v_mfma_f32_16x16x32_bf16 v[0:3], v[132:135], v[204:207], v[0:3]
	v_mfma_f32_16x16x32_bf16 v[8:11], v[136:139], v[200:203], v[8:11]
	v_mfma_f32_16x16x32_bf16 v[8:11], v[140:143], v[204:207], v[8:11]
	v_mfma_f32_16x16x32_bf16 v[24:27], v[136:139], v[192:195], v[24:27]
	v_mfma_f32_16x16x32_bf16 v[24:27], v[140:143], v[196:199], v[24:27]
	v_mfma_f32_16x16x32_bf16 v[40:43], v[136:139], v[184:187], v[40:43]
	v_mfma_f32_16x16x32_bf16 v[40:43], v[140:143], v[188:191], v[40:43]
	v_mfma_f32_16x16x32_bf16 v[56:59], v[136:139], v[176:179], v[56:59]
	v_mfma_f32_16x16x32_bf16 v[56:59], v[140:143], v[180:183], v[56:59]
	s_setprio 0
	s_setprio 1
	s_waitcnt lgkmcnt(0)
	v_mfma_f32_16x16x32_bf16 v[52:55], v[152:155], v[176:179], v[52:55]
	v_mfma_f32_16x16x32_bf16 v[52:55], v[156:159], v[180:183], v[52:55]
	v_mfma_f32_16x16x32_bf16 v[36:39], v[152:155], v[184:187], v[36:39]
	v_mfma_f32_16x16x32_bf16 v[36:39], v[156:159], v[188:191], v[36:39]
	v_mfma_f32_16x16x32_bf16 v[20:23], v[152:155], v[192:195], v[20:23]
	v_mfma_f32_16x16x32_bf16 v[20:23], v[156:159], v[196:199], v[20:23]
	v_mfma_f32_16x16x32_bf16 v[4:7], v[152:155], v[200:203], v[4:7]
	v_mfma_f32_16x16x32_bf16 v[4:7], v[156:159], v[204:207], v[4:7]
	v_mfma_f32_16x16x32_bf16 v[12:15], v[160:163], v[200:203], v[12:15]
	v_mfma_f32_16x16x32_bf16 v[12:15], v[172:175], v[204:207], v[12:15]
	v_mfma_f32_16x16x32_bf16 v[28:31], v[160:163], v[192:195], v[28:31]
	v_mfma_f32_16x16x32_bf16 v[28:31], v[172:175], v[196:199], v[28:31]
	v_mfma_f32_16x16x32_bf16 v[44:47], v[160:163], v[184:187], v[44:47]
	v_mfma_f32_16x16x32_bf16 v[44:47], v[172:175], v[188:191], v[44:47]
	v_mfma_f32_16x16x32_bf16 v[64:67], v[160:163], v[176:179], v[64:67]
	s_barrier
	v_mfma_f32_16x16x32_bf16 v[64:67], v[172:175], v[180:183], v[64:67]
	s_setprio 0
	ds_read_b128 v[128:131], v148
	ds_read_b128 v[132:135], v148 offset:1024
	ds_read_b128 v[136:139], v148 offset:2048
	ds_read_b128 v[140:143], v148 offset:3072
	ds_read_b128 v[152:155], v150
	ds_read_b128 v[156:159], v150 offset:1024
	ds_read_b128 v[160:163], v150 offset:2048
	ds_read_b128 v[172:175], v150 offset:3072
	ds_read_b128 v[176:179], v170 offset:32768
	ds_read_b128 v[180:183], v170 offset:33792
	ds_read_b128 v[184:187], v170 offset:34816
	ds_read_b128 v[188:191], v170 offset:35840
	ds_read_b128 v[192:195], v170 offset:36864
	ds_read_b128 v[196:199], v170 offset:37888
	ds_read_b128 v[200:203], v170 offset:38912
	ds_read_b128 v[204:207], v170 offset:39936
	s_add_u32 s52, s48, 0x4000
	s_addc_u32 s53, s49, 0
	s_mov_b32 m0, s61
	s_nop 0
	global_load_lds_dwordx4 v166, s[52:53]
	s_add_u32 s52, s48, 0x6000
	s_addc_u32 s53, s49, 0
	s_mov_b32 m0, s62
	s_nop 0
	global_load_lds_dwordx4 v166, s[52:53]
	s_waitcnt vmcnt(8)
	s_waitcnt lgkmcnt(0)
	s_barrier
	s_setprio 1
	s_waitcnt lgkmcnt(7)
	s_waitcnt lgkmcnt(0)
	v_mfma_f32_16x16x32_bf16 v[112:115], v[128:131], v[176:179], v[112:115]
	v_mfma_f32_16x16x32_bf16 v[112:115], v[132:135], v[180:183], v[112:115]
	v_mfma_f32_16x16x32_bf16 v[96:99], v[128:131], v[184:187], v[96:99]
	v_mfma_f32_16x16x32_bf16 v[96:99], v[132:135], v[188:191], v[96:99]
	v_mfma_f32_16x16x32_bf16 v[80:83], v[128:131], v[192:195], v[80:83]
	v_mfma_f32_16x16x32_bf16 v[80:83], v[132:135], v[196:199], v[80:83]
	v_mfma_f32_16x16x32_bf16 v[60:63], v[128:131], v[200:203], v[60:63]
	v_mfma_f32_16x16x32_bf16 v[60:63], v[132:135], v[204:207], v[60:63]
	v_mfma_f32_16x16x32_bf16 v[72:75], v[136:139], v[200:203], v[72:75]
	v_mfma_f32_16x16x32_bf16 v[72:75], v[140:143], v[204:207], v[72:75]
	v_mfma_f32_16x16x32_bf16 v[88:91], v[136:139], v[192:195], v[88:91]
	v_mfma_f32_16x16x32_bf16 v[88:91], v[140:143], v[196:199], v[88:91]
	v_mfma_f32_16x16x32_bf16 v[104:107], v[136:139], v[184:187], v[104:107]
	v_mfma_f32_16x16x32_bf16 v[104:107], v[140:143], v[188:191], v[104:107]
	v_mfma_f32_16x16x32_bf16 v[120:123], v[136:139], v[176:179], v[120:123]
	v_mfma_f32_16x16x32_bf16 v[120:123], v[140:143], v[180:183], v[120:123]
	s_setprio 0
	s_setprio 1
	s_waitcnt lgkmcnt(0)
	v_mfma_f32_16x16x32_bf16 v[116:119], v[152:155], v[176:179], v[116:119]
	v_mfma_f32_16x16x32_bf16 v[116:119], v[156:159], v[180:183], v[116:119]
	v_mfma_f32_16x16x32_bf16 v[100:103], v[152:155], v[184:187], v[100:103]
	v_mfma_f32_16x16x32_bf16 v[100:103], v[156:159], v[188:191], v[100:103]
	v_mfma_f32_16x16x32_bf16 v[84:87], v[152:155], v[192:195], v[84:87]
	v_mfma_f32_16x16x32_bf16 v[84:87], v[156:159], v[196:199], v[84:87]
	v_mfma_f32_16x16x32_bf16 v[68:71], v[152:155], v[200:203], v[68:71]
	v_mfma_f32_16x16x32_bf16 v[68:71], v[156:159], v[204:207], v[68:71]
	v_mfma_f32_16x16x32_bf16 v[76:79], v[160:163], v[200:203], v[76:79]
	v_mfma_f32_16x16x32_bf16 v[76:79], v[172:175], v[204:207], v[76:79]
	v_mfma_f32_16x16x32_bf16 v[92:95], v[160:163], v[192:195], v[92:95]
	v_mfma_f32_16x16x32_bf16 v[92:95], v[172:175], v[196:199], v[92:95]
	v_mfma_f32_16x16x32_bf16 v[108:111], v[160:163], v[184:187], v[108:111]
	v_mfma_f32_16x16x32_bf16 v[108:111], v[172:175], v[188:191], v[108:111]
	v_mfma_f32_16x16x32_bf16 v[124:127], v[160:163], v[176:179], v[124:127]
	s_barrier
	v_mfma_f32_16x16x32_bf16 v[124:127], v[172:175], v[180:183], v[124:127]
	s_setprio 0
	s_add_u32 s52, s90, 0xa000
	ds_read_b128 v[176:179], v170 offset:49152
	ds_read_b128 v[180:183], v170 offset:50176
	ds_read_b128 v[184:187], v170 offset:51200
	ds_read_b128 v[188:191], v170 offset:52224
	ds_read_b128 v[192:195], v170 offset:53248
	ds_read_b128 v[196:199], v170 offset:54272
	ds_read_b128 v[200:203], v170 offset:55296
	ds_read_b128 v[204:207], v170 offset:56320
	s_mov_b32 m0, s66
	s_nop 0
	global_load_lds_dwordx4 v166, s[92:93]
	s_addc_u32 s53, s91, 0
	s_mov_b32 m0, s67
	s_nop 0
	global_load_lds_dwordx4 v166, s[52:53]
	s_add_u32 s52, s90, 0xc000
	s_addc_u32 s53, s91, 0
	s_mov_b32 m0, s70
	s_nop 0
	global_load_lds_dwordx4 v166, s[52:53]
	s_add_u32 s52, s90, 0xe000
	s_addc_u32 s53, s91, 0
	s_mov_b32 m0, s71
	s_nop 0
	global_load_lds_dwordx4 v166, s[52:53]
	s_add_u32 s48, s48, 0xa000
	s_mov_b32 m0, s68
	s_nop 0
	global_load_lds_dwordx4 v166, s[80:81]
	s_addc_u32 s49, s49, 0
	s_mov_b32 m0, s69
	s_nop 0
	global_load_lds_dwordx4 v166, s[48:49]
	s_waitcnt vmcnt(8)
	s_waitcnt lgkmcnt(0)
	s_barrier
	s_setprio 1
	s_waitcnt lgkmcnt(7)
	s_waitcnt lgkmcnt(0)
	v_mfma_f32_16x16x32_bf16 v[48:51], v[128:131], v[176:179], v[48:51]
	v_mfma_f32_16x16x32_bf16 v[48:51], v[132:135], v[180:183], v[48:51]
	v_mfma_f32_16x16x32_bf16 v[32:35], v[128:131], v[184:187], v[32:35]
	v_mfma_f32_16x16x32_bf16 v[32:35], v[132:135], v[188:191], v[32:35]
	v_mfma_f32_16x16x32_bf16 v[16:19], v[128:131], v[192:195], v[16:19]
	v_mfma_f32_16x16x32_bf16 v[16:19], v[132:135], v[196:199], v[16:19]
	v_mfma_f32_16x16x32_bf16 v[0:3], v[128:131], v[200:203], v[0:3]
	v_mfma_f32_16x16x32_bf16 v[0:3], v[132:135], v[204:207], v[0:3]
	v_mfma_f32_16x16x32_bf16 v[8:11], v[136:139], v[200:203], v[8:11]
	v_mfma_f32_16x16x32_bf16 v[8:11], v[140:143], v[204:207], v[8:11]
	v_mfma_f32_16x16x32_bf16 v[24:27], v[136:139], v[192:195], v[24:27]
	v_mfma_f32_16x16x32_bf16 v[24:27], v[140:143], v[196:199], v[24:27]
	v_mfma_f32_16x16x32_bf16 v[40:43], v[136:139], v[184:187], v[40:43]
	v_mfma_f32_16x16x32_bf16 v[40:43], v[140:143], v[188:191], v[40:43]
	v_mfma_f32_16x16x32_bf16 v[56:59], v[136:139], v[176:179], v[56:59]
	v_mfma_f32_16x16x32_bf16 v[56:59], v[140:143], v[180:183], v[56:59]
	s_setprio 0
	s_setprio 1
	s_waitcnt lgkmcnt(0)
	v_mfma_f32_16x16x32_bf16 v[52:55], v[152:155], v[176:179], v[52:55]
	v_mfma_f32_16x16x32_bf16 v[52:55], v[156:159], v[180:183], v[52:55]
	v_mfma_f32_16x16x32_bf16 v[36:39], v[152:155], v[184:187], v[36:39]
	v_mfma_f32_16x16x32_bf16 v[36:39], v[156:159], v[188:191], v[36:39]
	v_mfma_f32_16x16x32_bf16 v[20:23], v[152:155], v[192:195], v[20:23]
	v_mfma_f32_16x16x32_bf16 v[20:23], v[156:159], v[196:199], v[20:23]
	v_mfma_f32_16x16x32_bf16 v[4:7], v[152:155], v[200:203], v[4:7]
	v_mfma_f32_16x16x32_bf16 v[4:7], v[156:159], v[204:207], v[4:7]
	v_mfma_f32_16x16x32_bf16 v[12:15], v[160:163], v[200:203], v[12:15]
	v_mfma_f32_16x16x32_bf16 v[12:15], v[172:175], v[204:207], v[12:15]
	v_mfma_f32_16x16x32_bf16 v[28:31], v[160:163], v[192:195], v[28:31]
	v_mfma_f32_16x16x32_bf16 v[28:31], v[172:175], v[196:199], v[28:31]
	v_mfma_f32_16x16x32_bf16 v[44:47], v[160:163], v[184:187], v[44:47]
	v_mfma_f32_16x16x32_bf16 v[44:47], v[172:175], v[188:191], v[44:47]
	v_mfma_f32_16x16x32_bf16 v[64:67], v[160:163], v[176:179], v[64:67]
	s_barrier
	v_mfma_f32_16x16x32_bf16 v[64:67], v[172:175], v[180:183], v[64:67]
	s_setprio 0
	s_add_i32 s88, s88, 2
	s_add_u32 s54, s54, 0x10000
	s_addc_u32 s55, s55, 0
	s_cmp_gt_u32 s88, 61
	s_mov_b64 s[52:53], s[2:3]
	s_cbranch_scc0 .LBB0_170
	s_nop 7
	s_and_b64 vcc, exec, s[12:13]
	s_cbranch_vccz .LBB0_173
	s_barrier

.LBB0_326:
	ds_read_b128 v[60:63], v212
	ds_read_b128 v[68:71], v212 offset:1024
	ds_read_b128 v[88:91], v212 offset:2048
	ds_read_b128 v[92:95], v212 offset:3072
	ds_read_b128 v[112:115], v213
	ds_read_b128 v[116:119], v213 offset:1024
	ds_read_b128 v[138:141], v213 offset:2048
	ds_read_b128 v[152:155], v213 offset:3072
	s_cmpk_eq_i32 s80, 0xa8
	s_cselect_b32 s2, s4, s76
	s_cselect_b32 s3, s5, s77
	s_cselect_b32 s42, s38, s78
	s_cselect_b32 s43, s39, s79
	s_add_u32 s40, s2, 0x8000
	s_addc_u32 s41, s3, 0
	ds_read_b128 v[164:167], v214
	ds_read_b128 v[168:171], v214 offset:1024
	ds_read_b128 v[172:175], v214 offset:2048
	ds_read_b128 v[176:179], v214 offset:3072
	ds_read_b128 v[180:183], v214 offset:4096
	ds_read_b128 v[184:187], v214 offset:5120
	ds_read_b128 v[188:191], v214 offset:6144
	ds_read_b128 v[192:195], v214 offset:7168
	s_add_u32 s44, s76, 0xffffc000
	s_addc_u32 s45, s77, -1
	s_mov_b32 m0, s65
	s_nop 0
	global_load_lds_dwordx4 v210, s[44:45]
	s_add_u32 s44, s76, 0xffffe000
	s_addc_u32 s45, s77, -1
	s_mov_b32 m0, s68
	s_nop 0
	global_load_lds_dwordx4 v210, s[44:45]
	s_waitcnt vmcnt(8)
	s_waitcnt lgkmcnt(0)
	s_add_u32 s44, s42, 0x8000
	s_addc_u32 s45, s43, 0
	s_barrier
	s_setprio 1
	s_waitcnt lgkmcnt(7)
	s_waitcnt lgkmcnt(0)
	v_mfma_f32_16x16x32_bf16 v[160:163], v[60:63], v[164:167], v[160:163]
	v_mfma_f32_16x16x32_bf16 v[160:163], v[68:71], v[168:171], v[160:163]
	v_mfma_f32_16x16x32_bf16 v[132:135], v[60:63], v[172:175], v[132:135]
	v_mfma_f32_16x16x32_bf16 v[132:135], v[68:71], v[176:179], v[132:135]
	v_mfma_f32_16x16x32_bf16 v[108:111], v[60:63], v[180:183], v[108:111]
	v_mfma_f32_16x16x32_bf16 v[108:111], v[68:71], v[184:187], v[108:111]
	v_mfma_f32_16x16x32_bf16 v[84:87], v[60:63], v[188:191], v[84:87]
	v_mfma_f32_16x16x32_bf16 v[84:87], v[68:71], v[192:195], v[84:87]
	v_mfma_f32_16x16x32_bf16 v[80:83], v[88:91], v[188:191], v[80:83]
	v_mfma_f32_16x16x32_bf16 v[80:83], v[92:95], v[192:195], v[80:83]
	v_mfma_f32_16x16x32_bf16 v[104:107], v[88:91], v[180:183], v[104:107]
	v_mfma_f32_16x16x32_bf16 v[104:107], v[92:95], v[184:187], v[104:107]
	v_mfma_f32_16x16x32_bf16 v[128:131], v[88:91], v[172:175], v[128:131]
	v_mfma_f32_16x16x32_bf16 v[128:131], v[92:95], v[176:179], v[128:131]
	v_mfma_f32_16x16x32_bf16 v[156:159], v[88:91], v[164:167], v[156:159]
	v_mfma_f32_16x16x32_bf16 v[156:159], v[92:95], v[168:171], v[156:159]
	s_setprio 0
	s_setprio 1
	v_mfma_f32_16x16x32_bf16 v[148:151], v[112:115], v[164:167], v[148:151]
	v_mfma_f32_16x16x32_bf16 v[142:145], v[138:141], v[164:167], v[144:147]
	v_mfma_f32_16x16x32_bf16 v[124:127], v[112:115], v[172:175], v[124:127]
	v_mfma_f32_16x16x32_bf16 v[120:123], v[138:141], v[172:175], v[120:123]
	v_mfma_f32_16x16x32_bf16 v[100:103], v[112:115], v[180:183], v[100:103]
	v_mfma_f32_16x16x32_bf16 v[96:99], v[138:141], v[180:183], v[96:99]
	v_mfma_f32_16x16x32_bf16 v[76:79], v[112:115], v[188:191], v[76:79]
	v_mfma_f32_16x16x32_bf16 v[72:75], v[138:141], v[188:191], v[72:75]
	v_mfma_f32_16x16x32_bf16 v[148:151], v[116:119], v[168:171], v[148:151]
	v_mfma_f32_16x16x32_bf16 v[142:145], v[152:155], v[168:171], v[142:145]
	v_mfma_f32_16x16x32_bf16 v[124:127], v[116:119], v[176:179], v[124:127]
	v_mfma_f32_16x16x32_bf16 v[120:123], v[152:155], v[176:179], v[120:123]
	v_mfma_f32_16x16x32_bf16 v[100:103], v[116:119], v[184:187], v[100:103]
	v_mfma_f32_16x16x32_bf16 v[96:99], v[152:155], v[184:187], v[96:99]
	v_mfma_f32_16x16x32_bf16 v[76:79], v[116:119], v[192:195], v[76:79]
	v_mfma_f32_16x16x32_bf16 v[72:75], v[152:155], v[192:195], v[72:75]
	s_setprio 0
	s_barrier
	s_add_u32 s82, s42, 0x2000
	ds_read_b128 v[164:167], v214 offset:16384
	ds_read_b128 v[168:171], v214 offset:17408
	ds_read_b128 v[172:175], v214 offset:18432
	ds_read_b128 v[176:179], v214 offset:19456
	ds_read_b128 v[180:183], v214 offset:20480
	ds_read_b128 v[184:187], v214 offset:21504
	ds_read_b128 v[188:191], v214 offset:22528
	ds_read_b128 v[192:195], v214 offset:23552
	s_mov_b32 m0, s47
	s_nop 0
	global_load_lds_dwordx4 v210, s[42:43]
	s_addc_u32 s83, s43, 0
	s_mov_b32 m0, s48
	s_nop 0
	global_load_lds_dwordx4 v210, s[82:83]
	s_add_u32 s82, s42, 0x4000
	s_addc_u32 s83, s43, 0
	s_mov_b32 m0, s49
	s_nop 0
	global_load_lds_dwordx4 v210, s[82:83]
	s_add_u32 s82, s42, 0x6000
	s_addc_u32 s83, s43, 0
	s_mov_b32 m0, s52
	s_nop 0
	global_load_lds_dwordx4 v210, s[82:83]
	s_add_u32 s82, s2, 0x2000
	s_mov_b32 m0, s46
	s_nop 0
	global_load_lds_dwordx4 v210, s[2:3]
	s_addc_u32 s83, s3, 0
	s_mov_b32 m0, s53
	s_nop 0
	global_load_lds_dwordx4 v210, s[82:83]
	s_waitcnt vmcnt(8)
	s_waitcnt lgkmcnt(0)
	s_barrier
	s_setprio 1
	s_waitcnt lgkmcnt(7)
	s_waitcnt lgkmcnt(0)
	v_mfma_f32_16x16x32_bf16 v[64:67], v[60:63], v[164:167], v[64:67]
	v_mfma_f32_16x16x32_bf16 v[64:67], v[68:71], v[168:171], v[64:67]
	v_mfma_f32_16x16x32_bf16 v[44:47], v[60:63], v[172:175], v[44:47]
	v_mfma_f32_16x16x32_bf16 v[44:47], v[68:71], v[176:179], v[44:47]
	v_mfma_f32_16x16x32_bf16 v[28:31], v[60:63], v[180:183], v[28:31]
	v_mfma_f32_16x16x32_bf16 v[28:31], v[68:71], v[184:187], v[28:31]
	v_mfma_f32_16x16x32_bf16 v[12:15], v[60:63], v[188:191], v[12:15]
	v_mfma_f32_16x16x32_bf16 v[12:15], v[68:71], v[192:195], v[12:15]
	v_mfma_f32_16x16x32_bf16 v[8:11], v[88:91], v[188:191], v[8:11]
	v_mfma_f32_16x16x32_bf16 v[8:11], v[92:95], v[192:195], v[8:11]
	v_mfma_f32_16x16x32_bf16 v[24:27], v[88:91], v[180:183], v[24:27]
	v_mfma_f32_16x16x32_bf16 v[24:27], v[92:95], v[184:187], v[24:27]
	v_mfma_f32_16x16x32_bf16 v[40:43], v[88:91], v[172:175], v[40:43]
	v_mfma_f32_16x16x32_bf16 v[40:43], v[92:95], v[176:179], v[40:43]
	v_mfma_f32_16x16x32_bf16 v[56:59], v[88:91], v[164:167], v[56:59]
	v_mfma_f32_16x16x32_bf16 v[56:59], v[92:95], v[168:171], v[56:59]
	s_setprio 0
	s_setprio 1
	s_waitcnt lgkmcnt(0)
	v_mfma_f32_16x16x32_bf16 v[52:55], v[112:115], v[164:167], v[52:55]
	v_mfma_f32_16x16x32_bf16 v[52:55], v[116:119], v[168:171], v[52:55]
	v_mfma_f32_16x16x32_bf16 v[36:39], v[112:115], v[172:175], v[36:39]
	v_mfma_f32_16x16x32_bf16 v[36:39], v[116:119], v[176:179], v[36:39]
	v_mfma_f32_16x16x32_bf16 v[20:23], v[112:115], v[180:183], v[20:23]
	v_mfma_f32_16x16x32_bf16 v[20:23], v[116:119], v[184:187], v[20:23]
	v_mfma_f32_16x16x32_bf16 v[4:7], v[112:115], v[188:191], v[4:7]
	v_mfma_f32_16x16x32_bf16 v[4:7], v[116:119], v[192:195], v[4:7]
	v_mfma_f32_16x16x32_bf16 v[0:3], v[138:141], v[188:191], v[0:3]
	v_mfma_f32_16x16x32_bf16 v[0:3], v[152:155], v[192:195], v[0:3]
	v_mfma_f32_16x16x32_bf16 v[16:19], v[138:141], v[180:183], v[16:19]
	v_mfma_f32_16x16x32_bf16 v[16:19], v[152:155], v[184:187], v[16:19]
	v_mfma_f32_16x16x32_bf16 v[32:35], v[138:141], v[172:175], v[32:35]
	v_mfma_f32_16x16x32_bf16 v[32:35], v[152:155], v[176:179], v[32:35]
	v_mfma_f32_16x16x32_bf16 v[48:51], v[138:141], v[164:167], v[48:51]
	s_barrier
	v_mfma_f32_16x16x32_bf16 v[48:51], v[152:155], v[168:171], v[48:51]
	s_setprio 0
	ds_read_b128 v[60:63], v136
	ds_read_b128 v[68:71], v136 offset:1024
	ds_read_b128 v[88:91], v136 offset:2048
	ds_read_b128 v[92:95], v136 offset:3072
	ds_read_b128 v[112:115], v137
	ds_read_b128 v[116:119], v137 offset:1024
	ds_read_b128 v[138:141], v137 offset:2048
	ds_read_b128 v[152:155], v137 offset:3072
	ds_read_b128 v[164:167], v214 offset:32768
	ds_read_b128 v[168:171], v214 offset:33792
	ds_read_b128 v[172:175], v214 offset:34816
	ds_read_b128 v[176:179], v214 offset:35840
	ds_read_b128 v[180:183], v214 offset:36864
	ds_read_b128 v[184:187], v214 offset:37888
	ds_read_b128 v[188:191], v214 offset:38912
	ds_read_b128 v[192:195], v214 offset:39936
	s_add_u32 s82, s2, 0x4000
	s_addc_u32 s83, s3, 0
	s_mov_b32 m0, s54
	s_nop 0
	global_load_lds_dwordx4 v210, s[82:83]
	s_add_u32 s82, s2, 0x6000
	s_addc_u32 s83, s3, 0
	s_mov_b32 m0, s55
	s_nop 0
	global_load_lds_dwordx4 v210, s[82:83]
	s_waitcnt vmcnt(8)
	s_waitcnt lgkmcnt(0)
	s_barrier
	s_setprio 1
	s_waitcnt lgkmcnt(7)
	s_waitcnt lgkmcnt(0)
	v_mfma_f32_16x16x32_bf16 v[160:163], v[60:63], v[164:167], v[160:163]
	v_mfma_f32_16x16x32_bf16 v[160:163], v[68:71], v[168:171], v[160:163]
	v_mfma_f32_16x16x32_bf16 v[132:135], v[60:63], v[172:175], v[132:135]
	v_mfma_f32_16x16x32_bf16 v[132:135], v[68:71], v[176:179], v[132:135]
	v_mfma_f32_16x16x32_bf16 v[108:111], v[60:63], v[180:183], v[108:111]
	v_mfma_f32_16x16x32_bf16 v[108:111], v[68:71], v[184:187], v[108:111]
	v_mfma_f32_16x16x32_bf16 v[84:87], v[60:63], v[188:191], v[84:87]
	v_mfma_f32_16x16x32_bf16 v[84:87], v[68:71], v[192:195], v[84:87]
	v_mfma_f32_16x16x32_bf16 v[80:83], v[88:91], v[188:191], v[80:83]
	v_mfma_f32_16x16x32_bf16 v[80:83], v[92:95], v[192:195], v[80:83]
	v_mfma_f32_16x16x32_bf16 v[104:107], v[88:91], v[180:183], v[104:107]
	v_mfma_f32_16x16x32_bf16 v[104:107], v[92:95], v[184:187], v[104:107]
	v_mfma_f32_16x16x32_bf16 v[128:131], v[88:91], v[172:175], v[128:131]
	v_mfma_f32_16x16x32_bf16 v[128:131], v[92:95], v[176:179], v[128:131]
	v_mfma_f32_16x16x32_bf16 v[156:159], v[88:91], v[164:167], v[156:159]
	v_mfma_f32_16x16x32_bf16 v[156:159], v[92:95], v[168:171], v[156:159]
	s_setprio 0
	s_setprio 1
	v_mfma_f32_16x16x32_bf16 v[146:149], v[112:115], v[164:167], v[148:151]
	v_mfma_f32_16x16x32_bf16 v[142:145], v[138:141], v[164:167], v[142:145]
	v_mfma_f32_16x16x32_bf16 v[124:127], v[112:115], v[172:175], v[124:127]
	v_mfma_f32_16x16x32_bf16 v[120:123], v[138:141], v[172:175], v[120:123]
	v_mfma_f32_16x16x32_bf16 v[100:103], v[112:115], v[180:183], v[100:103]
	v_mfma_f32_16x16x32_bf16 v[96:99], v[138:141], v[180:183], v[96:99]
	v_mfma_f32_16x16x32_bf16 v[76:79], v[112:115], v[188:191], v[76:79]
	v_mfma_f32_16x16x32_bf16 v[72:75], v[138:141], v[188:191], v[72:75]
	v_mfma_f32_16x16x32_bf16 v[148:151], v[116:119], v[168:171], v[146:149]
	v_mfma_f32_16x16x32_bf16 v[144:147], v[152:155], v[168:171], v[142:145]
	v_mfma_f32_16x16x32_bf16 v[124:127], v[116:119], v[176:179], v[124:127]
	v_mfma_f32_16x16x32_bf16 v[120:123], v[152:155], v[176:179], v[120:123]
	v_mfma_f32_16x16x32_bf16 v[100:103], v[116:119], v[184:187], v[100:103]
	v_mfma_f32_16x16x32_bf16 v[96:99], v[152:155], v[184:187], v[96:99]
	v_mfma_f32_16x16x32_bf16 v[76:79], v[116:119], v[192:195], v[76:79]
	v_mfma_f32_16x16x32_bf16 v[72:75], v[152:155], v[192:195], v[72:75]
	s_setprio 0
	s_barrier
	ds_read_b128 v[164:167], v214 offset:49152
	ds_read_b128 v[168:171], v214 offset:50176
	ds_read_b128 v[172:175], v214 offset:51200
	ds_read_b128 v[176:179], v214 offset:52224
	ds_read_b128 v[180:183], v214 offset:53248
	ds_read_b128 v[184:187], v214 offset:54272
	ds_read_b128 v[188:191], v214 offset:55296
	ds_read_b128 v[192:195], v214 offset:56320
	s_mov_b32 m0, s59
	s_nop 0
	global_load_lds_dwordx4 v210, s[44:45]
	s_add_u32 s44, s42, 0xa000
	s_addc_u32 s45, s43, 0
	s_mov_b32 m0, s60
	s_nop 0
	global_load_lds_dwordx4 v210, s[44:45]
	s_add_u32 s44, s42, 0xc000
	s_addc_u32 s45, s43, 0
	s_mov_b32 m0, s63
	s_nop 0
	global_load_lds_dwordx4 v210, s[44:45]
	s_add_u32 s42, s42, 0xe000
	s_addc_u32 s43, s43, 0
	s_mov_b32 m0, s64
	s_nop 0
	global_load_lds_dwordx4 v210, s[42:43]
	s_add_u32 s2, s2, 0xa000
	s_mov_b32 m0, s61
	s_nop 0
	global_load_lds_dwordx4 v210, s[40:41]
	s_addc_u32 s3, s3, 0
	s_mov_b32 m0, s62
	s_nop 0
	global_load_lds_dwordx4 v210, s[2:3]
	s_waitcnt vmcnt(8)
	s_waitcnt lgkmcnt(0)
	s_barrier
	s_setprio 1
	s_waitcnt lgkmcnt(7)
	s_waitcnt lgkmcnt(0)
	v_mfma_f32_16x16x32_bf16 v[64:67], v[60:63], v[164:167], v[64:67]
	v_mfma_f32_16x16x32_bf16 v[64:67], v[68:71], v[168:171], v[64:67]
	v_mfma_f32_16x16x32_bf16 v[44:47], v[60:63], v[172:175], v[44:47]
	v_mfma_f32_16x16x32_bf16 v[44:47], v[68:71], v[176:179], v[44:47]
	v_mfma_f32_16x16x32_bf16 v[28:31], v[60:63], v[180:183], v[28:31]
	v_mfma_f32_16x16x32_bf16 v[28:31], v[68:71], v[184:187], v[28:31]
	v_mfma_f32_16x16x32_bf16 v[12:15], v[60:63], v[188:191], v[12:15]
	v_mfma_f32_16x16x32_bf16 v[12:15], v[68:71], v[192:195], v[12:15]
	v_mfma_f32_16x16x32_bf16 v[8:11], v[88:91], v[188:191], v[8:11]
	v_mfma_f32_16x16x32_bf16 v[8:11], v[92:95], v[192:195], v[8:11]
	v_mfma_f32_16x16x32_bf16 v[24:27], v[88:91], v[180:183], v[24:27]
	v_mfma_f32_16x16x32_bf16 v[24:27], v[92:95], v[184:187], v[24:27]
	v_mfma_f32_16x16x32_bf16 v[40:43], v[88:91], v[172:175], v[40:43]
	v_mfma_f32_16x16x32_bf16 v[40:43], v[92:95], v[176:179], v[40:43]
	v_mfma_f32_16x16x32_bf16 v[56:59], v[88:91], v[164:167], v[56:59]
	v_mfma_f32_16x16x32_bf16 v[56:59], v[92:95], v[168:171], v[56:59]
	s_setprio 0
	s_setprio 1
	s_waitcnt lgkmcnt(0)
	v_mfma_f32_16x16x32_bf16 v[52:55], v[112:115], v[164:167], v[52:55]
	v_mfma_f32_16x16x32_bf16 v[52:55], v[116:119], v[168:171], v[52:55]
	v_mfma_f32_16x16x32_bf16 v[36:39], v[112:115], v[172:175], v[36:39]
	v_mfma_f32_16x16x32_bf16 v[36:39], v[116:119], v[176:179], v[36:39]
	v_mfma_f32_16x16x32_bf16 v[20:23], v[112:115], v[180:183], v[20:23]
	v_mfma_f32_16x16x32_bf16 v[20:23], v[116:119], v[184:187], v[20:23]
	v_mfma_f32_16x16x32_bf16 v[4:7], v[112:115], v[188:191], v[4:7]
	v_mfma_f32_16x16x32_bf16 v[4:7], v[116:119], v[192:195], v[4:7]
	v_mfma_f32_16x16x32_bf16 v[0:3], v[138:141], v[188:191], v[0:3]
	v_mfma_f32_16x16x32_bf16 v[0:3], v[152:155], v[192:195], v[0:3]
	v_mfma_f32_16x16x32_bf16 v[16:19], v[138:141], v[180:183], v[16:19]
	v_mfma_f32_16x16x32_bf16 v[16:19], v[152:155], v[184:187], v[16:19]
	v_mfma_f32_16x16x32_bf16 v[32:35], v[138:141], v[172:175], v[32:35]
	v_mfma_f32_16x16x32_bf16 v[32:35], v[152:155], v[176:179], v[32:35]
	v_mfma_f32_16x16x32_bf16 v[48:51], v[138:141], v[164:167], v[48:51]
	s_barrier
	v_mfma_f32_16x16x32_bf16 v[48:51], v[152:155], v[168:171], v[48:51]
	s_setprio 0
	s_add_i32 s80, s80, 2
	s_add_u32 s76, s76, 0x10000
	s_addc_u32 s77, s77, 0
	s_add_u32 s78, s78, 0x10000
	s_addc_u32 s79, s79, 0
	s_cmpk_gt_u32 s80, 0xa9
	s_cbranch_scc0 .LBB0_326
	s_nop 7
	s_and_b64 vcc, exec, s[12:13]
	s_cbranch_vccz .LBB0_329
	s_barrier

.LBB0_425:
	ds_read_b128 v[128:131], v162
	ds_read_b128 v[132:135], v162 offset:1024
	ds_read_b128 v[136:139], v162 offset:2048
	ds_read_b128 v[140:143], v162 offset:3072
	ds_read_b128 v[152:155], v163
	ds_read_b128 v[156:159], v163 offset:1024
	ds_read_b128 v[168:171], v163 offset:2048
	ds_read_b128 v[172:175], v163 offset:3072
	s_add_u32 s48, s52, 0x10000
	s_addc_u32 s49, s53, 0
	s_cmp_eq_u32 s79, 60
	s_cselect_b32 s80, s10, s48
	s_cselect_b32 s81, s5, s49
	s_cselect_b32 s96, s47, s77
	s_cselect_b32 s97, s45, s78
	s_add_u32 s2, s80, 0x8000
	s_addc_u32 s3, s81, 0
	ds_read_b128 v[176:179], v164
	ds_read_b128 v[180:183], v164 offset:1024
	ds_read_b128 v[184:187], v164 offset:2048
	ds_read_b128 v[188:191], v164 offset:3072
	ds_read_b128 v[192:195], v164 offset:4096
	ds_read_b128 v[196:199], v164 offset:5120
	ds_read_b128 v[200:203], v164 offset:6144
	ds_read_b128 v[204:207], v164 offset:7168
	s_add_u32 s82, s52, 0xc000
	s_addc_u32 s83, s53, 0
	s_mov_b32 m0, s70
	s_nop 0
	global_load_lds_dwordx4 v160, s[82:83]
	s_add_u32 s52, s52, 0xe000
	s_addc_u32 s53, s53, 0
	s_mov_b32 m0, s71
	s_nop 0
	global_load_lds_dwordx4 v160, s[52:53]
	s_waitcnt vmcnt(8)
	s_waitcnt lgkmcnt(0)
	s_add_u32 s52, s96, 0x8000
	s_addc_u32 s53, s97, 0
	s_barrier
	s_setprio 1
	s_waitcnt lgkmcnt(7)
	s_waitcnt lgkmcnt(0)
	v_mfma_f32_16x16x32_bf16 v[124:127], v[128:131], v[176:179], v[124:127]
	v_mfma_f32_16x16x32_bf16 v[124:127], v[132:135], v[180:183], v[124:127]
	v_mfma_f32_16x16x32_bf16 v[108:111], v[128:131], v[184:187], v[108:111]
	v_mfma_f32_16x16x32_bf16 v[108:111], v[132:135], v[188:191], v[108:111]
	v_mfma_f32_16x16x32_bf16 v[92:95], v[128:131], v[192:195], v[92:95]
	v_mfma_f32_16x16x32_bf16 v[92:95], v[132:135], v[196:199], v[92:95]
	v_mfma_f32_16x16x32_bf16 v[76:79], v[128:131], v[200:203], v[76:79]
	v_mfma_f32_16x16x32_bf16 v[76:79], v[132:135], v[204:207], v[76:79]
	v_mfma_f32_16x16x32_bf16 v[72:75], v[136:139], v[200:203], v[72:75]
	v_mfma_f32_16x16x32_bf16 v[72:75], v[140:143], v[204:207], v[72:75]
	v_mfma_f32_16x16x32_bf16 v[88:91], v[136:139], v[192:195], v[88:91]
	v_mfma_f32_16x16x32_bf16 v[88:91], v[140:143], v[196:199], v[88:91]
	v_mfma_f32_16x16x32_bf16 v[104:107], v[136:139], v[184:187], v[104:107]
	v_mfma_f32_16x16x32_bf16 v[104:107], v[140:143], v[188:191], v[104:107]
	v_mfma_f32_16x16x32_bf16 v[120:123], v[136:139], v[176:179], v[120:123]
	v_mfma_f32_16x16x32_bf16 v[120:123], v[140:143], v[180:183], v[120:123]
	s_setprio 0
	s_setprio 1
	s_waitcnt lgkmcnt(0)
	v_mfma_f32_16x16x32_bf16 v[116:119], v[152:155], v[176:179], v[116:119]
	v_mfma_f32_16x16x32_bf16 v[116:119], v[156:159], v[180:183], v[116:119]
	v_mfma_f32_16x16x32_bf16 v[100:103], v[152:155], v[184:187], v[100:103]
	v_mfma_f32_16x16x32_bf16 v[100:103], v[156:159], v[188:191], v[100:103]
	v_mfma_f32_16x16x32_bf16 v[84:87], v[152:155], v[192:195], v[84:87]
	v_mfma_f32_16x16x32_bf16 v[84:87], v[156:159], v[196:199], v[84:87]
	v_mfma_f32_16x16x32_bf16 v[68:71], v[152:155], v[200:203], v[68:71]
	v_mfma_f32_16x16x32_bf16 v[68:71], v[156:159], v[204:207], v[68:71]
	v_mfma_f32_16x16x32_bf16 v[64:67], v[168:171], v[200:203], v[64:67]
	v_mfma_f32_16x16x32_bf16 v[64:67], v[172:175], v[204:207], v[64:67]
	v_mfma_f32_16x16x32_bf16 v[80:83], v[168:171], v[192:195], v[80:83]
	v_mfma_f32_16x16x32_bf16 v[80:83], v[172:175], v[196:199], v[80:83]
	v_mfma_f32_16x16x32_bf16 v[96:99], v[168:171], v[184:187], v[96:99]
	v_mfma_f32_16x16x32_bf16 v[96:99], v[172:175], v[188:191], v[96:99]
	v_mfma_f32_16x16x32_bf16 v[112:115], v[168:171], v[176:179], v[112:115]
	s_barrier
	v_mfma_f32_16x16x32_bf16 v[112:115], v[172:175], v[180:183], v[112:115]
	s_setprio 0
	s_add_u32 s82, s96, 0x2000
	ds_read_b128 v[176:179], v164 offset:16384
	ds_read_b128 v[180:183], v164 offset:17408
	ds_read_b128 v[184:187], v164 offset:18432
	ds_read_b128 v[188:191], v164 offset:19456
	ds_read_b128 v[192:195], v164 offset:20480
	ds_read_b128 v[196:199], v164 offset:21504
	ds_read_b128 v[200:203], v164 offset:22528
	ds_read_b128 v[204:207], v164 offset:23552
	s_mov_b32 m0, s55
	s_nop 0
	global_load_lds_dwordx4 v160, s[96:97]
	s_addc_u32 s83, s97, 0
	s_mov_b32 m0, s56
	s_nop 0
	global_load_lds_dwordx4 v160, s[82:83]
	s_add_u32 s82, s96, 0x4000
	s_addc_u32 s83, s97, 0
	s_mov_b32 m0, s57
	s_nop 0
	global_load_lds_dwordx4 v160, s[82:83]
	s_add_u32 s82, s96, 0x6000
	s_addc_u32 s83, s97, 0
	s_mov_b32 m0, s58
	s_nop 0
	global_load_lds_dwordx4 v160, s[82:83]
	s_add_u32 s82, s80, 0x2000
	s_mov_b32 m0, s54
	s_nop 0
	global_load_lds_dwordx4 v160, s[80:81]
	s_addc_u32 s83, s81, 0
	s_mov_b32 m0, s59
	s_nop 0
	global_load_lds_dwordx4 v160, s[82:83]
	s_waitcnt vmcnt(8)
	s_waitcnt lgkmcnt(0)
	s_barrier
	s_setprio 1
	s_waitcnt lgkmcnt(7)
	s_waitcnt lgkmcnt(0)
	v_mfma_f32_16x16x32_bf16 v[60:63], v[128:131], v[176:179], v[60:63]
	v_mfma_f32_16x16x32_bf16 v[60:63], v[132:135], v[180:183], v[60:63]
	v_mfma_f32_16x16x32_bf16 v[44:47], v[128:131], v[184:187], v[44:47]
	v_mfma_f32_16x16x32_bf16 v[44:47], v[132:135], v[188:191], v[44:47]
	v_mfma_f32_16x16x32_bf16 v[28:31], v[128:131], v[192:195], v[28:31]
	v_mfma_f32_16x16x32_bf16 v[28:31], v[132:135], v[196:199], v[28:31]
	v_mfma_f32_16x16x32_bf16 v[12:15], v[128:131], v[200:203], v[12:15]
	v_mfma_f32_16x16x32_bf16 v[12:15], v[132:135], v[204:207], v[12:15]
	v_mfma_f32_16x16x32_bf16 v[8:11], v[136:139], v[200:203], v[8:11]
	v_mfma_f32_16x16x32_bf16 v[8:11], v[140:143], v[204:207], v[8:11]
	v_mfma_f32_16x16x32_bf16 v[24:27], v[136:139], v[192:195], v[24:27]
	v_mfma_f32_16x16x32_bf16 v[24:27], v[140:143], v[196:199], v[24:27]
	v_mfma_f32_16x16x32_bf16 v[40:43], v[136:139], v[184:187], v[40:43]
	v_mfma_f32_16x16x32_bf16 v[40:43], v[140:143], v[188:191], v[40:43]
	v_mfma_f32_16x16x32_bf16 v[56:59], v[136:139], v[176:179], v[56:59]
	v_mfma_f32_16x16x32_bf16 v[56:59], v[140:143], v[180:183], v[56:59]
	s_setprio 0
	s_setprio 1
	s_waitcnt lgkmcnt(0)
	v_mfma_f32_16x16x32_bf16 v[52:55], v[152:155], v[176:179], v[52:55]
	v_mfma_f32_16x16x32_bf16 v[52:55], v[156:159], v[180:183], v[52:55]
	v_mfma_f32_16x16x32_bf16 v[36:39], v[152:155], v[184:187], v[36:39]
	v_mfma_f32_16x16x32_bf16 v[36:39], v[156:159], v[188:191], v[36:39]
	v_mfma_f32_16x16x32_bf16 v[20:23], v[152:155], v[192:195], v[20:23]
	v_mfma_f32_16x16x32_bf16 v[20:23], v[156:159], v[196:199], v[20:23]
	v_mfma_f32_16x16x32_bf16 v[4:7], v[152:155], v[200:203], v[4:7]
	v_mfma_f32_16x16x32_bf16 v[4:7], v[156:159], v[204:207], v[4:7]
	v_mfma_f32_16x16x32_bf16 v[0:3], v[168:171], v[200:203], v[0:3]
	v_mfma_f32_16x16x32_bf16 v[0:3], v[172:175], v[204:207], v[0:3]
	v_mfma_f32_16x16x32_bf16 v[16:19], v[168:171], v[192:195], v[16:19]
	v_mfma_f32_16x16x32_bf16 v[16:19], v[172:175], v[196:199], v[16:19]
	v_mfma_f32_16x16x32_bf16 v[32:35], v[168:171], v[184:187], v[32:35]
	v_mfma_f32_16x16x32_bf16 v[32:35], v[172:175], v[188:191], v[32:35]
	v_mfma_f32_16x16x32_bf16 v[48:51], v[168:171], v[176:179], v[48:51]
	s_barrier
	v_mfma_f32_16x16x32_bf16 v[48:51], v[172:175], v[180:183], v[48:51]
	s_setprio 0
	ds_read_b128 v[128:131], v148
	ds_read_b128 v[132:135], v148 offset:1024
	ds_read_b128 v[136:139], v148 offset:2048
	ds_read_b128 v[140:143], v148 offset:3072
	ds_read_b128 v[152:155], v150
	ds_read_b128 v[156:159], v150 offset:1024
	ds_read_b128 v[168:171], v150 offset:2048
	ds_read_b128 v[172:175], v150 offset:3072
	ds_read_b128 v[176:179], v164 offset:32768
	ds_read_b128 v[180:183], v164 offset:33792
	ds_read_b128 v[184:187], v164 offset:34816
	ds_read_b128 v[188:191], v164 offset:35840
	ds_read_b128 v[192:195], v164 offset:36864
	ds_read_b128 v[196:199], v164 offset:37888
	ds_read_b128 v[200:203], v164 offset:38912
	ds_read_b128 v[204:207], v164 offset:39936
	s_add_u32 s82, s80, 0x4000
	s_addc_u32 s83, s81, 0
	s_mov_b32 m0, s60
	s_nop 0
	global_load_lds_dwordx4 v160, s[82:83]
	s_add_u32 s82, s80, 0x6000
	s_addc_u32 s83, s81, 0
	s_mov_b32 m0, s61
	s_nop 0
	global_load_lds_dwordx4 v160, s[82:83]
	s_waitcnt vmcnt(8)
	s_waitcnt lgkmcnt(0)
	s_barrier
	s_setprio 1
	s_waitcnt lgkmcnt(7)
	s_waitcnt lgkmcnt(0)
	v_mfma_f32_16x16x32_bf16 v[124:127], v[128:131], v[176:179], v[124:127]
	v_mfma_f32_16x16x32_bf16 v[124:127], v[132:135], v[180:183], v[124:127]
	v_mfma_f32_16x16x32_bf16 v[108:111], v[128:131], v[184:187], v[108:111]
	v_mfma_f32_16x16x32_bf16 v[108:111], v[132:135], v[188:191], v[108:111]
	v_mfma_f32_16x16x32_bf16 v[92:95], v[128:131], v[192:195], v[92:95]
	v_mfma_f32_16x16x32_bf16 v[92:95], v[132:135], v[196:199], v[92:95]
	v_mfma_f32_16x16x32_bf16 v[76:79], v[128:131], v[200:203], v[76:79]
	v_mfma_f32_16x16x32_bf16 v[76:79], v[132:135], v[204:207], v[76:79]
	v_mfma_f32_16x16x32_bf16 v[72:75], v[136:139], v[200:203], v[72:75]
	v_mfma_f32_16x16x32_bf16 v[72:75], v[140:143], v[204:207], v[72:75]
	v_mfma_f32_16x16x32_bf16 v[88:91], v[136:139], v[192:195], v[88:91]
	v_mfma_f32_16x16x32_bf16 v[88:91], v[140:143], v[196:199], v[88:91]
	v_mfma_f32_16x16x32_bf16 v[104:107], v[136:139], v[184:187], v[104:107]
	v_mfma_f32_16x16x32_bf16 v[104:107], v[140:143], v[188:191], v[104:107]
	v_mfma_f32_16x16x32_bf16 v[120:123], v[136:139], v[176:179], v[120:123]
	v_mfma_f32_16x16x32_bf16 v[120:123], v[140:143], v[180:183], v[120:123]
	s_setprio 0
	s_setprio 1
	s_waitcnt lgkmcnt(0)
	v_mfma_f32_16x16x32_bf16 v[116:119], v[152:155], v[176:179], v[116:119]
	v_mfma_f32_16x16x32_bf16 v[116:119], v[156:159], v[180:183], v[116:119]
	v_mfma_f32_16x16x32_bf16 v[100:103], v[152:155], v[184:187], v[100:103]
	v_mfma_f32_16x16x32_bf16 v[100:103], v[156:159], v[188:191], v[100:103]
	v_mfma_f32_16x16x32_bf16 v[84:87], v[152:155], v[192:195], v[84:87]
	v_mfma_f32_16x16x32_bf16 v[84:87], v[156:159], v[196:199], v[84:87]
	v_mfma_f32_16x16x32_bf16 v[68:71], v[152:155], v[200:203], v[68:71]
	v_mfma_f32_16x16x32_bf16 v[68:71], v[156:159], v[204:207], v[68:71]
	v_mfma_f32_16x16x32_bf16 v[64:67], v[168:171], v[200:203], v[64:67]
	v_mfma_f32_16x16x32_bf16 v[64:67], v[172:175], v[204:207], v[64:67]
	v_mfma_f32_16x16x32_bf16 v[80:83], v[168:171], v[192:195], v[80:83]
	v_mfma_f32_16x16x32_bf16 v[80:83], v[172:175], v[196:199], v[80:83]
	v_mfma_f32_16x16x32_bf16 v[96:99], v[168:171], v[184:187], v[96:99]
	v_mfma_f32_16x16x32_bf16 v[96:99], v[172:175], v[188:191], v[96:99]
	v_mfma_f32_16x16x32_bf16 v[112:115], v[168:171], v[176:179], v[112:115]
	s_barrier
	v_mfma_f32_16x16x32_bf16 v[112:115], v[172:175], v[180:183], v[112:115]
	s_setprio 0
	ds_read_b128 v[176:179], v164 offset:49152
	ds_read_b128 v[180:183], v164 offset:50176
	ds_read_b128 v[184:187], v164 offset:51200
	ds_read_b128 v[188:191], v164 offset:52224
	ds_read_b128 v[192:195], v164 offset:53248
	ds_read_b128 v[196:199], v164 offset:54272
	ds_read_b128 v[200:203], v164 offset:55296
	ds_read_b128 v[204:207], v164 offset:56320
	s_mov_b32 m0, s64
	s_nop 0
	global_load_lds_dwordx4 v160, s[52:53]
	s_add_u32 s52, s96, 0xa000
	s_addc_u32 s53, s97, 0
	s_mov_b32 m0, s65
	s_nop 0
	global_load_lds_dwordx4 v160, s[52:53]
	s_add_u32 s52, s96, 0xc000
	s_addc_u32 s53, s97, 0
	s_mov_b32 m0, s68
	s_nop 0
	global_load_lds_dwordx4 v160, s[52:53]
	s_add_u32 s52, s96, 0xe000
	s_addc_u32 s53, s97, 0
	s_mov_b32 m0, s69
	s_nop 0
	global_load_lds_dwordx4 v160, s[52:53]
	s_nop 0
	s_mov_b32 m0, s66
	s_nop 0
	global_load_lds_dwordx4 v160, s[2:3]
	s_add_u32 s2, s80, 0xa000
	s_addc_u32 s3, s81, 0
	s_mov_b32 m0, s67
	s_nop 0
	global_load_lds_dwordx4 v160, s[2:3]
	s_waitcnt vmcnt(8)
	s_waitcnt lgkmcnt(0)
	s_barrier
	s_setprio 1
	s_waitcnt lgkmcnt(7)
	s_waitcnt lgkmcnt(0)
	v_mfma_f32_16x16x32_bf16 v[60:63], v[128:131], v[176:179], v[60:63]
	v_mfma_f32_16x16x32_bf16 v[60:63], v[132:135], v[180:183], v[60:63]
	v_mfma_f32_16x16x32_bf16 v[44:47], v[128:131], v[184:187], v[44:47]
	v_mfma_f32_16x16x32_bf16 v[44:47], v[132:135], v[188:191], v[44:47]
	v_mfma_f32_16x16x32_bf16 v[28:31], v[128:131], v[192:195], v[28:31]
	v_mfma_f32_16x16x32_bf16 v[28:31], v[132:135], v[196:199], v[28:31]
	v_mfma_f32_16x16x32_bf16 v[12:15], v[128:131], v[200:203], v[12:15]
	v_mfma_f32_16x16x32_bf16 v[12:15], v[132:135], v[204:207], v[12:15]
	v_mfma_f32_16x16x32_bf16 v[8:11], v[136:139], v[200:203], v[8:11]
	v_mfma_f32_16x16x32_bf16 v[8:11], v[140:143], v[204:207], v[8:11]
	v_mfma_f32_16x16x32_bf16 v[24:27], v[136:139], v[192:195], v[24:27]
	v_mfma_f32_16x16x32_bf16 v[24:27], v[140:143], v[196:199], v[24:27]
	v_mfma_f32_16x16x32_bf16 v[40:43], v[136:139], v[184:187], v[40:43]
	v_mfma_f32_16x16x32_bf16 v[40:43], v[140:143], v[188:191], v[40:43]
	v_mfma_f32_16x16x32_bf16 v[56:59], v[136:139], v[176:179], v[56:59]
	v_mfma_f32_16x16x32_bf16 v[56:59], v[140:143], v[180:183], v[56:59]
	s_setprio 0
	s_setprio 1
	s_waitcnt lgkmcnt(0)
	v_mfma_f32_16x16x32_bf16 v[52:55], v[152:155], v[176:179], v[52:55]
	v_mfma_f32_16x16x32_bf16 v[52:55], v[156:159], v[180:183], v[52:55]
	v_mfma_f32_16x16x32_bf16 v[36:39], v[152:155], v[184:187], v[36:39]
	v_mfma_f32_16x16x32_bf16 v[36:39], v[156:159], v[188:191], v[36:39]
	v_mfma_f32_16x16x32_bf16 v[20:23], v[152:155], v[192:195], v[20:23]
	v_mfma_f32_16x16x32_bf16 v[20:23], v[156:159], v[196:199], v[20:23]
	v_mfma_f32_16x16x32_bf16 v[4:7], v[152:155], v[200:203], v[4:7]
	v_mfma_f32_16x16x32_bf16 v[4:7], v[156:159], v[204:207], v[4:7]
	v_mfma_f32_16x16x32_bf16 v[0:3], v[168:171], v[200:203], v[0:3]
	v_mfma_f32_16x16x32_bf16 v[0:3], v[172:175], v[204:207], v[0:3]
	v_mfma_f32_16x16x32_bf16 v[16:19], v[168:171], v[192:195], v[16:19]
	v_mfma_f32_16x16x32_bf16 v[16:19], v[172:175], v[196:199], v[16:19]
	v_mfma_f32_16x16x32_bf16 v[32:35], v[168:171], v[184:187], v[32:35]
	v_mfma_f32_16x16x32_bf16 v[32:35], v[172:175], v[188:191], v[32:35]
	v_mfma_f32_16x16x32_bf16 v[48:51], v[168:171], v[176:179], v[48:51]
	s_barrier
	v_mfma_f32_16x16x32_bf16 v[48:51], v[172:175], v[180:183], v[48:51]
	s_setprio 0
	s_add_i32 s79, s79, 2
	s_add_u32 s77, s77, 0x10000
	s_addc_u32 s78, s78, 0
	s_cmp_gt_u32 s79, 61
	s_mov_b64 s[52:53], s[48:49]
	s_cbranch_scc0 .LBB0_425
	s_nop 7
	s_and_b64 vcc, exec, s[14:15]
	s_cbranch_vccz .LBB0_428
	s_barrier

.LBB0_1406:
	ds_read_b128 v[72:75], v212
	ds_read_b128 v[84:87], v212 offset:1024
	ds_read_b128 v[96:99], v212 offset:2048
	ds_read_b128 v[108:111], v212 offset:3072
	ds_read_b128 v[112:115], v213
	ds_read_b128 v[136:139], v213 offset:1024
	ds_read_b128 v[148:151], v213 offset:2048
	ds_read_b128 v[160:163], v213 offset:3072
	s_cmp_eq_u32 s90, 60
	s_cselect_b32 s2, s82, s54
	s_cselect_b32 s3, s41, s55
	s_cselect_b32 s58, s83, s88
	s_cselect_b32 s59, s39, s89
	s_add_u32 s56, s2, 0x8000
	s_addc_u32 s57, s3, 0
	ds_read_b128 v[164:167], v214
	ds_read_b128 v[168:171], v214 offset:1024
	ds_read_b128 v[172:175], v214 offset:2048
	ds_read_b128 v[176:179], v214 offset:3072
	ds_read_b128 v[180:183], v214 offset:4096
	ds_read_b128 v[184:187], v214 offset:5120
	ds_read_b128 v[188:191], v214 offset:6144
	ds_read_b128 v[192:195], v214 offset:7168
	s_add_u32 s52, s54, 0xffffc000
	s_addc_u32 s53, s55, -1
	s_mov_b32 m0, s75
	s_nop 0
	global_load_lds_dwordx4 v210, s[52:53]
	s_add_u32 s52, s54, 0xffffe000
	s_addc_u32 s53, s55, -1
	s_mov_b32 m0, s78
	s_nop 0
	global_load_lds_dwordx4 v210, s[52:53]
	s_waitcnt vmcnt(8)
	s_waitcnt lgkmcnt(0)
	s_add_u32 s52, s58, 0x8000
	s_addc_u32 s53, s59, 0
	s_barrier
	s_setprio 1
	s_waitcnt lgkmcnt(7)
	v_mfma_f32_16x16x32_bf16 v[156:159], v[72:75], v[164:167], v[156:159]
	v_mfma_f32_16x16x32_bf16 v[152:155], v[96:99], v[164:167], v[152:155]
	s_waitcnt lgkmcnt(5)
	v_mfma_f32_16x16x32_bf16 v[132:135], v[72:75], v[172:175], v[132:135]
	v_mfma_f32_16x16x32_bf16 v[126:129], v[96:99], v[172:175], v[128:131]
	s_waitcnt lgkmcnt(3)
	v_mfma_f32_16x16x32_bf16 v[104:107], v[72:75], v[180:183], v[104:107]
	v_mfma_f32_16x16x32_bf16 v[100:103], v[96:99], v[180:183], v[100:103]
	s_waitcnt lgkmcnt(1)
	v_mfma_f32_16x16x32_bf16 v[80:83], v[72:75], v[188:191], v[80:83]
	v_mfma_f32_16x16x32_bf16 v[76:79], v[96:99], v[188:191], v[76:79]
	v_mfma_f32_16x16x32_bf16 v[156:159], v[84:87], v[168:171], v[156:159]
	v_mfma_f32_16x16x32_bf16 v[152:155], v[108:111], v[168:171], v[152:155]
	v_mfma_f32_16x16x32_bf16 v[132:135], v[84:87], v[176:179], v[132:135]
	v_mfma_f32_16x16x32_bf16 v[126:129], v[108:111], v[176:179], v[126:129]
	v_mfma_f32_16x16x32_bf16 v[104:107], v[84:87], v[184:187], v[104:107]
	v_mfma_f32_16x16x32_bf16 v[100:103], v[108:111], v[184:187], v[100:103]
	s_waitcnt lgkmcnt(0)
	v_mfma_f32_16x16x32_bf16 v[80:83], v[84:87], v[192:195], v[80:83]
	v_mfma_f32_16x16x32_bf16 v[76:79], v[108:111], v[192:195], v[76:79]
	s_setprio 0
	s_setprio 1
	s_waitcnt lgkmcnt(0)
	v_mfma_f32_16x16x32_bf16 v[144:147], v[112:115], v[164:167], v[144:147]
	v_mfma_f32_16x16x32_bf16 v[144:147], v[136:139], v[168:171], v[144:147]
	v_mfma_f32_16x16x32_bf16 v[120:123], v[112:115], v[172:175], v[120:123]
	v_mfma_f32_16x16x32_bf16 v[120:123], v[136:139], v[176:179], v[120:123]
	v_mfma_f32_16x16x32_bf16 v[92:95], v[112:115], v[180:183], v[92:95]
	v_mfma_f32_16x16x32_bf16 v[92:95], v[136:139], v[184:187], v[92:95]
	v_mfma_f32_16x16x32_bf16 v[68:71], v[112:115], v[188:191], v[68:71]
	v_mfma_f32_16x16x32_bf16 v[68:71], v[136:139], v[192:195], v[68:71]
	v_mfma_f32_16x16x32_bf16 v[64:67], v[148:151], v[188:191], v[64:67]
	v_mfma_f32_16x16x32_bf16 v[64:67], v[160:163], v[192:195], v[64:67]
	v_mfma_f32_16x16x32_bf16 v[88:91], v[148:151], v[180:183], v[88:91]
	v_mfma_f32_16x16x32_bf16 v[88:91], v[160:163], v[184:187], v[88:91]
	v_mfma_f32_16x16x32_bf16 v[116:119], v[148:151], v[172:175], v[116:119]
	v_mfma_f32_16x16x32_bf16 v[116:119], v[160:163], v[176:179], v[116:119]
	v_mfma_f32_16x16x32_bf16 v[140:143], v[148:151], v[164:167], v[140:143]
	s_barrier
	v_mfma_f32_16x16x32_bf16 v[140:143], v[160:163], v[168:171], v[140:143]
	s_setprio 0
	s_add_u32 s92, s58, 0x2000
	ds_read_b128 v[164:167], v214 offset:16384
	ds_read_b128 v[168:171], v214 offset:17408
	ds_read_b128 v[172:175], v214 offset:18432
	ds_read_b128 v[176:179], v214 offset:19456
	ds_read_b128 v[180:183], v214 offset:20480
	ds_read_b128 v[184:187], v214 offset:21504
	ds_read_b128 v[188:191], v214 offset:22528
	ds_read_b128 v[192:195], v214 offset:23552
	s_mov_b32 m0, s47
	s_nop 0
	global_load_lds_dwordx4 v210, s[58:59]
	s_addc_u32 s93, s59, 0
	s_mov_b32 m0, s49
	s_nop 0
	global_load_lds_dwordx4 v210, s[92:93]
	s_add_u32 s92, s58, 0x4000
	s_addc_u32 s93, s59, 0
	s_mov_b32 m0, s61
	s_nop 0
	global_load_lds_dwordx4 v210, s[92:93]
	s_add_u32 s92, s58, 0x6000
	s_addc_u32 s93, s59, 0
	s_mov_b32 m0, s62
	s_nop 0
	global_load_lds_dwordx4 v210, s[92:93]
	s_add_u32 s92, s2, 0x2000
	s_mov_b32 m0, s60
	s_nop 0
	global_load_lds_dwordx4 v210, s[2:3]
	s_addc_u32 s93, s3, 0
	s_mov_b32 m0, s63
	s_nop 0
	global_load_lds_dwordx4 v210, s[92:93]
	s_waitcnt vmcnt(8)
	s_waitcnt lgkmcnt(0)
	s_barrier
	s_setprio 1
	s_waitcnt lgkmcnt(7)
	s_waitcnt lgkmcnt(0)
	v_mfma_f32_16x16x32_bf16 v[60:63], v[72:75], v[164:167], v[60:63]
	v_mfma_f32_16x16x32_bf16 v[60:63], v[84:87], v[168:171], v[60:63]
	v_mfma_f32_16x16x32_bf16 v[44:47], v[72:75], v[172:175], v[44:47]
	v_mfma_f32_16x16x32_bf16 v[44:47], v[84:87], v[176:179], v[44:47]
	v_mfma_f32_16x16x32_bf16 v[28:31], v[72:75], v[180:183], v[28:31]
	v_mfma_f32_16x16x32_bf16 v[28:31], v[84:87], v[184:187], v[28:31]
	v_mfma_f32_16x16x32_bf16 v[12:15], v[72:75], v[188:191], v[12:15]
	v_mfma_f32_16x16x32_bf16 v[12:15], v[84:87], v[192:195], v[12:15]
	v_mfma_f32_16x16x32_bf16 v[8:11], v[96:99], v[188:191], v[8:11]
	v_mfma_f32_16x16x32_bf16 v[8:11], v[108:111], v[192:195], v[8:11]
	v_mfma_f32_16x16x32_bf16 v[24:27], v[96:99], v[180:183], v[24:27]
	v_mfma_f32_16x16x32_bf16 v[24:27], v[108:111], v[184:187], v[24:27]
	v_mfma_f32_16x16x32_bf16 v[40:43], v[96:99], v[172:175], v[40:43]
	v_mfma_f32_16x16x32_bf16 v[40:43], v[108:111], v[176:179], v[40:43]
	v_mfma_f32_16x16x32_bf16 v[56:59], v[96:99], v[164:167], v[56:59]
	v_mfma_f32_16x16x32_bf16 v[56:59], v[108:111], v[168:171], v[56:59]
	s_setprio 0
	s_setprio 1
	s_waitcnt lgkmcnt(0)
	v_mfma_f32_16x16x32_bf16 v[52:55], v[112:115], v[164:167], v[52:55]
	v_mfma_f32_16x16x32_bf16 v[52:55], v[136:139], v[168:171], v[52:55]
	v_mfma_f32_16x16x32_bf16 v[36:39], v[112:115], v[172:175], v[36:39]
	v_mfma_f32_16x16x32_bf16 v[36:39], v[136:139], v[176:179], v[36:39]
	v_mfma_f32_16x16x32_bf16 v[20:23], v[112:115], v[180:183], v[20:23]
	v_mfma_f32_16x16x32_bf16 v[20:23], v[136:139], v[184:187], v[20:23]
	v_mfma_f32_16x16x32_bf16 v[4:7], v[112:115], v[188:191], v[4:7]
	v_mfma_f32_16x16x32_bf16 v[4:7], v[136:139], v[192:195], v[4:7]
	v_mfma_f32_16x16x32_bf16 v[0:3], v[148:151], v[188:191], v[0:3]
	v_mfma_f32_16x16x32_bf16 v[0:3], v[160:163], v[192:195], v[0:3]
	v_mfma_f32_16x16x32_bf16 v[16:19], v[148:151], v[180:183], v[16:19]
	v_mfma_f32_16x16x32_bf16 v[16:19], v[160:163], v[184:187], v[16:19]
	v_mfma_f32_16x16x32_bf16 v[32:35], v[148:151], v[172:175], v[32:35]
	v_mfma_f32_16x16x32_bf16 v[32:35], v[160:163], v[176:179], v[32:35]
	v_mfma_f32_16x16x32_bf16 v[48:51], v[148:151], v[164:167], v[48:51]
	s_barrier
	v_mfma_f32_16x16x32_bf16 v[48:51], v[160:163], v[168:171], v[48:51]
	s_setprio 0
	ds_read_b128 v[72:75], v124
	ds_read_b128 v[84:87], v124 offset:1024
	ds_read_b128 v[96:99], v124 offset:2048
	ds_read_b128 v[108:111], v124 offset:3072
	ds_read_b128 v[112:115], v125
	ds_read_b128 v[136:139], v125 offset:1024
	ds_read_b128 v[148:151], v125 offset:2048
	ds_read_b128 v[160:163], v125 offset:3072
	ds_read_b128 v[164:167], v214 offset:32768
	ds_read_b128 v[168:171], v214 offset:33792
	ds_read_b128 v[172:175], v214 offset:34816
	ds_read_b128 v[176:179], v214 offset:35840
	ds_read_b128 v[180:183], v214 offset:36864
	ds_read_b128 v[184:187], v214 offset:37888
	ds_read_b128 v[188:191], v214 offset:38912
	ds_read_b128 v[192:195], v214 offset:39936
	s_add_u32 s92, s2, 0x4000
	s_addc_u32 s93, s3, 0
	s_mov_b32 m0, s64
	s_nop 0
	global_load_lds_dwordx4 v210, s[92:93]
	s_add_u32 s92, s2, 0x6000
	s_addc_u32 s93, s3, 0
	s_mov_b32 m0, s65
	s_nop 0
	global_load_lds_dwordx4 v210, s[92:93]
	s_waitcnt vmcnt(8)
	s_waitcnt lgkmcnt(0)
	s_barrier
	s_setprio 1
	s_waitcnt lgkmcnt(7)
	v_mfma_f32_16x16x32_bf16 v[156:159], v[72:75], v[164:167], v[156:159]
	v_mfma_f32_16x16x32_bf16 v[152:155], v[96:99], v[164:167], v[152:155]
	s_waitcnt lgkmcnt(5)
	v_mfma_f32_16x16x32_bf16 v[130:133], v[72:75], v[172:175], v[132:135]
	v_mfma_f32_16x16x32_bf16 v[126:129], v[96:99], v[172:175], v[126:129]
	s_waitcnt lgkmcnt(3)
	v_mfma_f32_16x16x32_bf16 v[104:107], v[72:75], v[180:183], v[104:107]
	v_mfma_f32_16x16x32_bf16 v[100:103], v[96:99], v[180:183], v[100:103]
	s_waitcnt lgkmcnt(1)
	v_mfma_f32_16x16x32_bf16 v[80:83], v[72:75], v[188:191], v[80:83]
	v_mfma_f32_16x16x32_bf16 v[76:79], v[96:99], v[188:191], v[76:79]
	v_mfma_f32_16x16x32_bf16 v[156:159], v[84:87], v[168:171], v[156:159]
	v_mfma_f32_16x16x32_bf16 v[152:155], v[108:111], v[168:171], v[152:155]
	v_mfma_f32_16x16x32_bf16 v[132:135], v[84:87], v[176:179], v[130:133]
	v_mfma_f32_16x16x32_bf16 v[128:131], v[108:111], v[176:179], v[126:129]
	v_mfma_f32_16x16x32_bf16 v[104:107], v[84:87], v[184:187], v[104:107]
	v_mfma_f32_16x16x32_bf16 v[100:103], v[108:111], v[184:187], v[100:103]
	s_waitcnt lgkmcnt(0)
	v_mfma_f32_16x16x32_bf16 v[80:83], v[84:87], v[192:195], v[80:83]
	v_mfma_f32_16x16x32_bf16 v[76:79], v[108:111], v[192:195], v[76:79]
	s_setprio 0
	s_setprio 1
	s_waitcnt lgkmcnt(0)
	v_mfma_f32_16x16x32_bf16 v[144:147], v[112:115], v[164:167], v[144:147]
	v_mfma_f32_16x16x32_bf16 v[144:147], v[136:139], v[168:171], v[144:147]
	v_mfma_f32_16x16x32_bf16 v[120:123], v[112:115], v[172:175], v[120:123]
	v_mfma_f32_16x16x32_bf16 v[120:123], v[136:139], v[176:179], v[120:123]
	v_mfma_f32_16x16x32_bf16 v[92:95], v[112:115], v[180:183], v[92:95]
	v_mfma_f32_16x16x32_bf16 v[92:95], v[136:139], v[184:187], v[92:95]
	v_mfma_f32_16x16x32_bf16 v[68:71], v[112:115], v[188:191], v[68:71]
	v_mfma_f32_16x16x32_bf16 v[68:71], v[136:139], v[192:195], v[68:71]
	v_mfma_f32_16x16x32_bf16 v[64:67], v[148:151], v[188:191], v[64:67]
	v_mfma_f32_16x16x32_bf16 v[64:67], v[160:163], v[192:195], v[64:67]
	v_mfma_f32_16x16x32_bf16 v[88:91], v[148:151], v[180:183], v[88:91]
	v_mfma_f32_16x16x32_bf16 v[88:91], v[160:163], v[184:187], v[88:91]
	v_mfma_f32_16x16x32_bf16 v[116:119], v[148:151], v[172:175], v[116:119]
	v_mfma_f32_16x16x32_bf16 v[116:119], v[160:163], v[176:179], v[116:119]
	v_mfma_f32_16x16x32_bf16 v[140:143], v[148:151], v[164:167], v[140:143]
	s_barrier
	v_mfma_f32_16x16x32_bf16 v[140:143], v[160:163], v[168:171], v[140:143]
	s_setprio 0
	ds_read_b128 v[164:167], v214 offset:49152
	ds_read_b128 v[168:171], v214 offset:50176
	ds_read_b128 v[172:175], v214 offset:51200
	ds_read_b128 v[176:179], v214 offset:52224
	ds_read_b128 v[180:183], v214 offset:53248
	ds_read_b128 v[184:187], v214 offset:54272
	ds_read_b128 v[188:191], v214 offset:55296
	ds_read_b128 v[192:195], v214 offset:56320
	s_mov_b32 m0, s69
	s_nop 0
	global_load_lds_dwordx4 v210, s[52:53]
	s_add_u32 s52, s58, 0xa000
	s_addc_u32 s53, s59, 0
	s_mov_b32 m0, s70
	s_nop 0
	global_load_lds_dwordx4 v210, s[52:53]
	s_add_u32 s52, s58, 0xc000
	s_addc_u32 s53, s59, 0
	s_mov_b32 m0, s73
	s_nop 0
	global_load_lds_dwordx4 v210, s[52:53]
	s_add_u32 s52, s58, 0xe000
	s_addc_u32 s53, s59, 0
	s_mov_b32 m0, s74
	s_nop 0
	global_load_lds_dwordx4 v210, s[52:53]
	s_add_u32 s2, s2, 0xa000
	s_mov_b32 m0, s71
	s_nop 0
	global_load_lds_dwordx4 v210, s[56:57]
	s_addc_u32 s3, s3, 0
	s_mov_b32 m0, s72
	s_nop 0
	global_load_lds_dwordx4 v210, s[2:3]
	s_waitcnt vmcnt(8)
	s_waitcnt lgkmcnt(0)
	s_barrier
	s_setprio 1
	s_waitcnt lgkmcnt(7)
	s_waitcnt lgkmcnt(0)
	v_mfma_f32_16x16x32_bf16 v[60:63], v[72:75], v[164:167], v[60:63]
	v_mfma_f32_16x16x32_bf16 v[60:63], v[84:87], v[168:171], v[60:63]
	v_mfma_f32_16x16x32_bf16 v[44:47], v[72:75], v[172:175], v[44:47]
	v_mfma_f32_16x16x32_bf16 v[44:47], v[84:87], v[176:179], v[44:47]
	v_mfma_f32_16x16x32_bf16 v[28:31], v[72:75], v[180:183], v[28:31]
	v_mfma_f32_16x16x32_bf16 v[28:31], v[84:87], v[184:187], v[28:31]
	v_mfma_f32_16x16x32_bf16 v[12:15], v[72:75], v[188:191], v[12:15]
	v_mfma_f32_16x16x32_bf16 v[12:15], v[84:87], v[192:195], v[12:15]
	v_mfma_f32_16x16x32_bf16 v[8:11], v[96:99], v[188:191], v[8:11]
	v_mfma_f32_16x16x32_bf16 v[8:11], v[108:111], v[192:195], v[8:11]
	v_mfma_f32_16x16x32_bf16 v[24:27], v[96:99], v[180:183], v[24:27]
	v_mfma_f32_16x16x32_bf16 v[24:27], v[108:111], v[184:187], v[24:27]
	v_mfma_f32_16x16x32_bf16 v[40:43], v[96:99], v[172:175], v[40:43]
	v_mfma_f32_16x16x32_bf16 v[40:43], v[108:111], v[176:179], v[40:43]
	v_mfma_f32_16x16x32_bf16 v[56:59], v[96:99], v[164:167], v[56:59]
	v_mfma_f32_16x16x32_bf16 v[56:59], v[108:111], v[168:171], v[56:59]
	s_setprio 0
	s_setprio 1
	s_waitcnt lgkmcnt(0)
	v_mfma_f32_16x16x32_bf16 v[52:55], v[112:115], v[164:167], v[52:55]
	v_mfma_f32_16x16x32_bf16 v[52:55], v[136:139], v[168:171], v[52:55]
	v_mfma_f32_16x16x32_bf16 v[36:39], v[112:115], v[172:175], v[36:39]
	v_mfma_f32_16x16x32_bf16 v[36:39], v[136:139], v[176:179], v[36:39]
	v_mfma_f32_16x16x32_bf16 v[20:23], v[112:115], v[180:183], v[20:23]
	v_mfma_f32_16x16x32_bf16 v[20:23], v[136:139], v[184:187], v[20:23]
	v_mfma_f32_16x16x32_bf16 v[4:7], v[112:115], v[188:191], v[4:7]
	v_mfma_f32_16x16x32_bf16 v[4:7], v[136:139], v[192:195], v[4:7]
	v_mfma_f32_16x16x32_bf16 v[0:3], v[148:151], v[188:191], v[0:3]
	v_mfma_f32_16x16x32_bf16 v[0:3], v[160:163], v[192:195], v[0:3]
	v_mfma_f32_16x16x32_bf16 v[16:19], v[148:151], v[180:183], v[16:19]
	v_mfma_f32_16x16x32_bf16 v[16:19], v[160:163], v[184:187], v[16:19]
	v_mfma_f32_16x16x32_bf16 v[32:35], v[148:151], v[172:175], v[32:35]
	v_mfma_f32_16x16x32_bf16 v[32:35], v[160:163], v[176:179], v[32:35]
	v_mfma_f32_16x16x32_bf16 v[48:51], v[148:151], v[164:167], v[48:51]
	s_barrier
	v_mfma_f32_16x16x32_bf16 v[48:51], v[160:163], v[168:171], v[48:51]
	s_setprio 0
	s_add_i32 s90, s90, 2
	s_add_u32 s54, s54, 0x10000
	s_addc_u32 s55, s55, 0
	s_add_u32 s88, s88, 0x10000
	s_addc_u32 s89, s89, 0
	s_cmp_gt_u32 s90, 61
	s_cbranch_scc0 .LBB0_1406
	s_nop 7
	s_and_b64 vcc, exec, s[12:13]
	s_cbranch_vccz .LBB0_1409
	s_barrier

.LBB0_1505:
	ds_read_b128 v[128:131], v156
	ds_read_b128 v[132:135], v156 offset:1024
	ds_read_b128 v[136:139], v156 offset:2048
	ds_read_b128 v[140:143], v156 offset:3072
	ds_read_b128 v[146:149], v157
	ds_read_b128 v[162:165], v157 offset:1024
	ds_read_b128 v[166:169], v157 offset:2048
	ds_read_b128 v[170:173], v157 offset:3072
	s_add_u32 s2, s52, 0x10000
	s_addc_u32 s3, s53, 0
	s_cmp_eq_u32 s96, 60
	s_cselect_b32 s58, s92, s2
	s_cselect_b32 s59, s45, s3
	s_cselect_b32 s64, s93, s54
	s_cselect_b32 s65, s43, s55
	s_add_u32 s60, s58, 0x8000
	s_addc_u32 s61, s59, 0
	ds_read_b128 v[174:177], v158
	ds_read_b128 v[178:181], v158 offset:1024
	ds_read_b128 v[182:185], v158 offset:2048
	ds_read_b128 v[186:189], v158 offset:3072
	ds_read_b128 v[190:193], v158 offset:4096
	ds_read_b128 v[194:197], v158 offset:5120
	ds_read_b128 v[198:201], v158 offset:6144
	ds_read_b128 v[202:205], v158 offset:7168
	s_add_u32 s12, s52, 0xc000
	s_addc_u32 s13, s53, 0
	s_mov_b32 m0, s81
	s_nop 0
	global_load_lds_dwordx4 v154, s[12:13]
	s_add_u32 s12, s52, 0xe000
	s_addc_u32 s13, s53, 0
	s_mov_b32 m0, s82
	s_nop 0
	global_load_lds_dwordx4 v154, s[12:13]
	s_waitcnt vmcnt(8)
	s_waitcnt lgkmcnt(0)
	s_add_u32 s52, s64, 0x8000
	s_addc_u32 s53, s65, 0
	s_barrier
	s_setprio 1
	s_waitcnt lgkmcnt(7)
	s_waitcnt lgkmcnt(0)
	v_mfma_f32_16x16x32_bf16 v[116:119], v[128:131], v[174:177], v[116:119]
	v_mfma_f32_16x16x32_bf16 v[116:119], v[132:135], v[178:181], v[116:119]
	v_mfma_f32_16x16x32_bf16 v[100:103], v[128:131], v[182:185], v[100:103]
	v_mfma_f32_16x16x32_bf16 v[100:103], v[132:135], v[186:189], v[100:103]
	v_mfma_f32_16x16x32_bf16 v[92:95], v[128:131], v[190:193], v[92:95]
	v_mfma_f32_16x16x32_bf16 v[92:95], v[132:135], v[194:197], v[92:95]
	v_mfma_f32_16x16x32_bf16 v[76:79], v[128:131], v[198:201], v[76:79]
	v_mfma_f32_16x16x32_bf16 v[76:79], v[132:135], v[202:205], v[76:79]
	v_mfma_f32_16x16x32_bf16 v[72:75], v[136:139], v[198:201], v[72:75]
	v_mfma_f32_16x16x32_bf16 v[72:75], v[140:143], v[202:205], v[72:75]
	v_mfma_f32_16x16x32_bf16 v[88:91], v[136:139], v[190:193], v[88:91]
	v_mfma_f32_16x16x32_bf16 v[88:91], v[140:143], v[194:197], v[88:91]
	v_mfma_f32_16x16x32_bf16 v[96:99], v[136:139], v[182:185], v[96:99]
	v_mfma_f32_16x16x32_bf16 v[96:99], v[140:143], v[186:189], v[96:99]
	v_mfma_f32_16x16x32_bf16 v[112:115], v[136:139], v[174:177], v[112:115]
	v_mfma_f32_16x16x32_bf16 v[112:115], v[140:143], v[178:181], v[112:115]
	s_setprio 0
	s_setprio 1
	s_waitcnt lgkmcnt(0)
	v_mfma_f32_16x16x32_bf16 v[124:127], v[146:149], v[174:177], v[124:127]
	v_mfma_f32_16x16x32_bf16 v[124:127], v[162:165], v[178:181], v[124:127]
	v_mfma_f32_16x16x32_bf16 v[108:111], v[146:149], v[182:185], v[108:111]
	v_mfma_f32_16x16x32_bf16 v[108:111], v[162:165], v[186:189], v[108:111]
	v_mfma_f32_16x16x32_bf16 v[84:87], v[146:149], v[190:193], v[84:87]
	v_mfma_f32_16x16x32_bf16 v[84:87], v[162:165], v[194:197], v[84:87]
	v_mfma_f32_16x16x32_bf16 v[68:71], v[146:149], v[198:201], v[68:71]
	v_mfma_f32_16x16x32_bf16 v[68:71], v[162:165], v[202:205], v[68:71]
	v_mfma_f32_16x16x32_bf16 v[64:67], v[166:169], v[198:201], v[64:67]
	v_mfma_f32_16x16x32_bf16 v[64:67], v[170:173], v[202:205], v[64:67]
	v_mfma_f32_16x16x32_bf16 v[80:83], v[166:169], v[190:193], v[80:83]
	v_mfma_f32_16x16x32_bf16 v[80:83], v[170:173], v[194:197], v[80:83]
	v_mfma_f32_16x16x32_bf16 v[104:107], v[166:169], v[182:185], v[104:107]
	v_mfma_f32_16x16x32_bf16 v[104:107], v[170:173], v[186:189], v[104:107]
	v_mfma_f32_16x16x32_bf16 v[120:123], v[166:169], v[174:177], v[120:123]
	s_barrier
	v_mfma_f32_16x16x32_bf16 v[120:123], v[170:173], v[178:181], v[120:123]
	s_setprio 0
	s_add_u32 s12, s64, 0x2000
	ds_read_b128 v[174:177], v158 offset:16384
	ds_read_b128 v[178:181], v158 offset:17408
	ds_read_b128 v[182:185], v158 offset:18432
	ds_read_b128 v[186:189], v158 offset:19456
	ds_read_b128 v[190:193], v158 offset:20480
	ds_read_b128 v[194:197], v158 offset:21504
	ds_read_b128 v[198:201], v158 offset:22528
	ds_read_b128 v[202:205], v158 offset:23552
	s_mov_b32 m0, s57
	s_nop 0
	global_load_lds_dwordx4 v154, s[64:65]
	s_addc_u32 s13, s65, 0
	s_mov_b32 m0, s67
	s_nop 0
	global_load_lds_dwordx4 v154, s[12:13]
	s_add_u32 s12, s64, 0x4000
	s_addc_u32 s13, s65, 0
	s_mov_b32 m0, s68
	s_nop 0
	global_load_lds_dwordx4 v154, s[12:13]
	s_add_u32 s12, s64, 0x6000
	s_addc_u32 s13, s65, 0
	s_mov_b32 m0, s69
	s_nop 0
	global_load_lds_dwordx4 v154, s[12:13]
	s_add_u32 s12, s58, 0x2000
	s_mov_b32 m0, s66
	s_nop 0
	global_load_lds_dwordx4 v154, s[58:59]
	s_addc_u32 s13, s59, 0
	s_mov_b32 m0, s70
	s_nop 0
	global_load_lds_dwordx4 v154, s[12:13]
	s_waitcnt vmcnt(8)
	s_waitcnt lgkmcnt(0)
	s_barrier
	s_setprio 1
	s_waitcnt lgkmcnt(7)
	s_waitcnt lgkmcnt(0)
	v_mfma_f32_16x16x32_bf16 v[60:63], v[128:131], v[174:177], v[60:63]
	v_mfma_f32_16x16x32_bf16 v[60:63], v[132:135], v[178:181], v[60:63]
	v_mfma_f32_16x16x32_bf16 v[44:47], v[128:131], v[182:185], v[44:47]
	v_mfma_f32_16x16x32_bf16 v[44:47], v[132:135], v[186:189], v[44:47]
	v_mfma_f32_16x16x32_bf16 v[28:31], v[128:131], v[190:193], v[28:31]
	v_mfma_f32_16x16x32_bf16 v[28:31], v[132:135], v[194:197], v[28:31]
	v_mfma_f32_16x16x32_bf16 v[12:15], v[128:131], v[198:201], v[12:15]
	v_mfma_f32_16x16x32_bf16 v[12:15], v[132:135], v[202:205], v[12:15]
	v_mfma_f32_16x16x32_bf16 v[8:11], v[136:139], v[198:201], v[8:11]
	v_mfma_f32_16x16x32_bf16 v[8:11], v[140:143], v[202:205], v[8:11]
	v_mfma_f32_16x16x32_bf16 v[24:27], v[136:139], v[190:193], v[24:27]
	v_mfma_f32_16x16x32_bf16 v[24:27], v[140:143], v[194:197], v[24:27]
	v_mfma_f32_16x16x32_bf16 v[40:43], v[136:139], v[182:185], v[40:43]
	v_mfma_f32_16x16x32_bf16 v[40:43], v[140:143], v[186:189], v[40:43]
	v_mfma_f32_16x16x32_bf16 v[56:59], v[136:139], v[174:177], v[56:59]
	v_mfma_f32_16x16x32_bf16 v[56:59], v[140:143], v[178:181], v[56:59]
	s_setprio 0
	s_setprio 1
	s_waitcnt lgkmcnt(0)
	v_mfma_f32_16x16x32_bf16 v[52:55], v[146:149], v[174:177], v[52:55]
	v_mfma_f32_16x16x32_bf16 v[52:55], v[162:165], v[178:181], v[52:55]
	v_mfma_f32_16x16x32_bf16 v[36:39], v[146:149], v[182:185], v[36:39]
	v_mfma_f32_16x16x32_bf16 v[36:39], v[162:165], v[186:189], v[36:39]
	v_mfma_f32_16x16x32_bf16 v[20:23], v[146:149], v[190:193], v[20:23]
	v_mfma_f32_16x16x32_bf16 v[20:23], v[162:165], v[194:197], v[20:23]
	v_mfma_f32_16x16x32_bf16 v[4:7], v[146:149], v[198:201], v[4:7]
	v_mfma_f32_16x16x32_bf16 v[4:7], v[162:165], v[202:205], v[4:7]
	v_mfma_f32_16x16x32_bf16 v[0:3], v[166:169], v[198:201], v[0:3]
	v_mfma_f32_16x16x32_bf16 v[0:3], v[170:173], v[202:205], v[0:3]
	v_mfma_f32_16x16x32_bf16 v[16:19], v[166:169], v[190:193], v[16:19]
	v_mfma_f32_16x16x32_bf16 v[16:19], v[170:173], v[194:197], v[16:19]
	v_mfma_f32_16x16x32_bf16 v[32:35], v[166:169], v[182:185], v[32:35]
	v_mfma_f32_16x16x32_bf16 v[32:35], v[170:173], v[186:189], v[32:35]
	v_mfma_f32_16x16x32_bf16 v[48:51], v[166:169], v[174:177], v[48:51]
	s_barrier
	v_mfma_f32_16x16x32_bf16 v[48:51], v[170:173], v[178:181], v[48:51]
	s_setprio 0
	ds_read_b128 v[128:131], v144
	ds_read_b128 v[132:135], v144 offset:1024
	ds_read_b128 v[136:139], v144 offset:2048
	ds_read_b128 v[140:143], v144 offset:3072
	ds_read_b128 v[146:149], v150
	ds_read_b128 v[162:165], v150 offset:1024
	ds_read_b128 v[166:169], v150 offset:2048
	ds_read_b128 v[170:173], v150 offset:3072
	ds_read_b128 v[174:177], v158 offset:32768
	ds_read_b128 v[178:181], v158 offset:33792
	ds_read_b128 v[182:185], v158 offset:34816
	ds_read_b128 v[186:189], v158 offset:35840
	ds_read_b128 v[190:193], v158 offset:36864
	ds_read_b128 v[194:197], v158 offset:37888
	ds_read_b128 v[198:201], v158 offset:38912
	ds_read_b128 v[202:205], v158 offset:39936
	s_add_u32 s12, s58, 0x4000
	s_addc_u32 s13, s59, 0
	s_mov_b32 m0, s71
	s_nop 0
	global_load_lds_dwordx4 v154, s[12:13]
	s_add_u32 s12, s58, 0x6000
	s_addc_u32 s13, s59, 0
	s_mov_b32 m0, s72
	s_nop 0
	global_load_lds_dwordx4 v154, s[12:13]
	s_waitcnt vmcnt(8)
	s_waitcnt lgkmcnt(0)
	s_barrier
	s_setprio 1
	s_waitcnt lgkmcnt(7)
	s_waitcnt lgkmcnt(0)
	v_mfma_f32_16x16x32_bf16 v[116:119], v[128:131], v[174:177], v[116:119]
	v_mfma_f32_16x16x32_bf16 v[116:119], v[132:135], v[178:181], v[116:119]
	v_mfma_f32_16x16x32_bf16 v[100:103], v[128:131], v[182:185], v[100:103]
	v_mfma_f32_16x16x32_bf16 v[100:103], v[132:135], v[186:189], v[100:103]
	v_mfma_f32_16x16x32_bf16 v[92:95], v[128:131], v[190:193], v[92:95]
	v_mfma_f32_16x16x32_bf16 v[92:95], v[132:135], v[194:197], v[92:95]
	v_mfma_f32_16x16x32_bf16 v[76:79], v[128:131], v[198:201], v[76:79]
	v_mfma_f32_16x16x32_bf16 v[76:79], v[132:135], v[202:205], v[76:79]
	v_mfma_f32_16x16x32_bf16 v[72:75], v[136:139], v[198:201], v[72:75]
	v_mfma_f32_16x16x32_bf16 v[72:75], v[140:143], v[202:205], v[72:75]
	v_mfma_f32_16x16x32_bf16 v[88:91], v[136:139], v[190:193], v[88:91]
	v_mfma_f32_16x16x32_bf16 v[88:91], v[140:143], v[194:197], v[88:91]
	v_mfma_f32_16x16x32_bf16 v[96:99], v[136:139], v[182:185], v[96:99]
	v_mfma_f32_16x16x32_bf16 v[96:99], v[140:143], v[186:189], v[96:99]
	v_mfma_f32_16x16x32_bf16 v[112:115], v[136:139], v[174:177], v[112:115]
	v_mfma_f32_16x16x32_bf16 v[112:115], v[140:143], v[178:181], v[112:115]
	s_setprio 0
	s_setprio 1
	s_waitcnt lgkmcnt(0)
	v_mfma_f32_16x16x32_bf16 v[124:127], v[146:149], v[174:177], v[124:127]
	v_mfma_f32_16x16x32_bf16 v[124:127], v[162:165], v[178:181], v[124:127]
	v_mfma_f32_16x16x32_bf16 v[108:111], v[146:149], v[182:185], v[108:111]
	v_mfma_f32_16x16x32_bf16 v[108:111], v[162:165], v[186:189], v[108:111]
	v_mfma_f32_16x16x32_bf16 v[84:87], v[146:149], v[190:193], v[84:87]
	v_mfma_f32_16x16x32_bf16 v[84:87], v[162:165], v[194:197], v[84:87]
	v_mfma_f32_16x16x32_bf16 v[68:71], v[146:149], v[198:201], v[68:71]
	v_mfma_f32_16x16x32_bf16 v[68:71], v[162:165], v[202:205], v[68:71]
	v_mfma_f32_16x16x32_bf16 v[64:67], v[166:169], v[198:201], v[64:67]
	v_mfma_f32_16x16x32_bf16 v[64:67], v[170:173], v[202:205], v[64:67]
	v_mfma_f32_16x16x32_bf16 v[80:83], v[166:169], v[190:193], v[80:83]
	v_mfma_f32_16x16x32_bf16 v[80:83], v[170:173], v[194:197], v[80:83]
	v_mfma_f32_16x16x32_bf16 v[104:107], v[166:169], v[182:185], v[104:107]
	v_mfma_f32_16x16x32_bf16 v[104:107], v[170:173], v[186:189], v[104:107]
	v_mfma_f32_16x16x32_bf16 v[120:123], v[166:169], v[174:177], v[120:123]
	s_barrier
	v_mfma_f32_16x16x32_bf16 v[120:123], v[170:173], v[178:181], v[120:123]
	s_setprio 0
	s_add_u32 s12, s64, 0xa000
	ds_read_b128 v[174:177], v158 offset:49152
	ds_read_b128 v[178:181], v158 offset:50176
	ds_read_b128 v[182:185], v158 offset:51200
	ds_read_b128 v[186:189], v158 offset:52224
	ds_read_b128 v[190:193], v158 offset:53248
	ds_read_b128 v[194:197], v158 offset:54272
	ds_read_b128 v[198:201], v158 offset:55296
	ds_read_b128 v[202:205], v158 offset:56320
	s_mov_b32 m0, s75
	s_nop 0
	global_load_lds_dwordx4 v154, s[52:53]
	s_addc_u32 s13, s65, 0
	s_mov_b32 m0, s76
	s_nop 0
	global_load_lds_dwordx4 v154, s[12:13]
	s_add_u32 s12, s64, 0xc000
	s_addc_u32 s13, s65, 0
	s_mov_b32 m0, s79
	s_nop 0
	global_load_lds_dwordx4 v154, s[12:13]
	s_add_u32 s12, s64, 0xe000
	s_addc_u32 s13, s65, 0
	s_mov_b32 m0, s80
	s_nop 0
	global_load_lds_dwordx4 v154, s[12:13]
	s_add_u32 s12, s58, 0xa000
	s_mov_b32 m0, s77
	s_nop 0
	global_load_lds_dwordx4 v154, s[60:61]
	s_addc_u32 s13, s59, 0
	s_mov_b32 m0, s78
	s_nop 0
	global_load_lds_dwordx4 v154, s[12:13]
	s_waitcnt vmcnt(8)
	s_waitcnt lgkmcnt(0)
	s_barrier
	s_setprio 1
	s_waitcnt lgkmcnt(7)
	s_waitcnt lgkmcnt(0)
	v_mfma_f32_16x16x32_bf16 v[60:63], v[128:131], v[174:177], v[60:63]
	v_mfma_f32_16x16x32_bf16 v[60:63], v[132:135], v[178:181], v[60:63]
	v_mfma_f32_16x16x32_bf16 v[44:47], v[128:131], v[182:185], v[44:47]
	v_mfma_f32_16x16x32_bf16 v[44:47], v[132:135], v[186:189], v[44:47]
	v_mfma_f32_16x16x32_bf16 v[28:31], v[128:131], v[190:193], v[28:31]
	v_mfma_f32_16x16x32_bf16 v[28:31], v[132:135], v[194:197], v[28:31]
	v_mfma_f32_16x16x32_bf16 v[12:15], v[128:131], v[198:201], v[12:15]
	v_mfma_f32_16x16x32_bf16 v[12:15], v[132:135], v[202:205], v[12:15]
	v_mfma_f32_16x16x32_bf16 v[8:11], v[136:139], v[198:201], v[8:11]
	v_mfma_f32_16x16x32_bf16 v[8:11], v[140:143], v[202:205], v[8:11]
	v_mfma_f32_16x16x32_bf16 v[24:27], v[136:139], v[190:193], v[24:27]
	v_mfma_f32_16x16x32_bf16 v[24:27], v[140:143], v[194:197], v[24:27]
	v_mfma_f32_16x16x32_bf16 v[40:43], v[136:139], v[182:185], v[40:43]
	v_mfma_f32_16x16x32_bf16 v[40:43], v[140:143], v[186:189], v[40:43]
	v_mfma_f32_16x16x32_bf16 v[56:59], v[136:139], v[174:177], v[56:59]
	v_mfma_f32_16x16x32_bf16 v[56:59], v[140:143], v[178:181], v[56:59]
	s_setprio 0
	s_setprio 1
	s_waitcnt lgkmcnt(0)
	v_mfma_f32_16x16x32_bf16 v[52:55], v[146:149], v[174:177], v[52:55]
	v_mfma_f32_16x16x32_bf16 v[52:55], v[162:165], v[178:181], v[52:55]
	v_mfma_f32_16x16x32_bf16 v[36:39], v[146:149], v[182:185], v[36:39]
	v_mfma_f32_16x16x32_bf16 v[36:39], v[162:165], v[186:189], v[36:39]
	v_mfma_f32_16x16x32_bf16 v[20:23], v[146:149], v[190:193], v[20:23]
	v_mfma_f32_16x16x32_bf16 v[20:23], v[162:165], v[194:197], v[20:23]
	v_mfma_f32_16x16x32_bf16 v[4:7], v[146:149], v[198:201], v[4:7]
	v_mfma_f32_16x16x32_bf16 v[4:7], v[162:165], v[202:205], v[4:7]
	v_mfma_f32_16x16x32_bf16 v[0:3], v[166:169], v[198:201], v[0:3]
	v_mfma_f32_16x16x32_bf16 v[0:3], v[170:173], v[202:205], v[0:3]
	v_mfma_f32_16x16x32_bf16 v[16:19], v[166:169], v[190:193], v[16:19]
	v_mfma_f32_16x16x32_bf16 v[16:19], v[170:173], v[194:197], v[16:19]
	v_mfma_f32_16x16x32_bf16 v[32:35], v[166:169], v[182:185], v[32:35]
	v_mfma_f32_16x16x32_bf16 v[32:35], v[170:173], v[186:189], v[32:35]
	v_mfma_f32_16x16x32_bf16 v[48:51], v[166:169], v[174:177], v[48:51]
	s_barrier
	v_mfma_f32_16x16x32_bf16 v[48:51], v[170:173], v[178:181], v[48:51]
	s_setprio 0
	s_add_i32 s96, s96, 2
	s_add_u32 s54, s54, 0x10000
	s_addc_u32 s55, s55, 0
	s_cmp_gt_u32 s96, 61
	s_mov_b64 s[52:53], s[2:3]
	s_cbranch_scc0 .LBB0_1505
	s_nop 7
	s_and_b64 vcc, exec, s[40:41]
	s_cbranch_vccz .LBB0_1508
	s_barrier

.LBB0_1539:
	ds_read_b128 v[128:131], v138
	ds_read_b128 v[132:135], v138 offset:1024
	ds_read_b128 v[144:147], v138 offset:2048
	ds_read_b128 v[148:151], v138 offset:3072
	ds_read_b128 v[152:155], v139
	ds_read_b128 v[156:159], v139 offset:1024
	ds_read_b128 v[160:163], v139 offset:2048
	ds_read_b128 v[164:167], v139 offset:3072
	s_add_u32 s2, s52, 0x10000
	s_addc_u32 s3, s53, 0
	s_cmp_eq_u32 s83, 60
	s_cselect_b32 s46, s79, s2
	s_cselect_b32 s47, s39, s3
	s_cselect_b32 s56, s80, s81
	s_cselect_b32 s57, s15, s82
	s_add_u32 s48, s46, 0x8000
	s_addc_u32 s49, s47, 0
	ds_read_b128 v[168:171], v140
	ds_read_b128 v[172:175], v140 offset:1024
	ds_read_b128 v[176:179], v140 offset:2048
	ds_read_b128 v[180:183], v140 offset:3072
	ds_read_b128 v[184:187], v140 offset:4096
	ds_read_b128 v[188:191], v140 offset:5120
	ds_read_b128 v[192:195], v140 offset:6144
	ds_read_b128 v[196:199], v140 offset:7168
	s_add_u32 s88, s52, 0xc000
	s_addc_u32 s89, s53, 0
	s_mov_b32 m0, s74
	s_nop 0
	global_load_lds_dwordx4 v136, s[88:89]
	s_add_u32 s52, s52, 0xe000
	s_addc_u32 s53, s53, 0
	s_mov_b32 m0, s75
	s_nop 0
	global_load_lds_dwordx4 v136, s[52:53]
	s_waitcnt vmcnt(8)
	s_waitcnt lgkmcnt(0)
	s_add_u32 s52, s56, 0x8000
	s_addc_u32 s53, s57, 0
	s_barrier
	s_setprio 1
	s_waitcnt lgkmcnt(7)
	s_waitcnt lgkmcnt(0)
	v_mfma_f32_16x16x32_bf16 v[120:123], v[128:131], v[168:171], v[120:123]
	v_mfma_f32_16x16x32_bf16 v[120:123], v[132:135], v[172:175], v[120:123]
	v_mfma_f32_16x16x32_bf16 v[104:107], v[128:131], v[176:179], v[104:107]
	v_mfma_f32_16x16x32_bf16 v[104:107], v[132:135], v[180:183], v[104:107]
	v_mfma_f32_16x16x32_bf16 v[84:87], v[128:131], v[184:187], v[84:87]
	v_mfma_f32_16x16x32_bf16 v[84:87], v[132:135], v[188:191], v[84:87]
	v_mfma_f32_16x16x32_bf16 v[52:55], v[128:131], v[192:195], v[52:55]
	v_mfma_f32_16x16x32_bf16 v[52:55], v[132:135], v[196:199], v[52:55]
	v_mfma_f32_16x16x32_bf16 v[36:39], v[144:147], v[192:195], v[36:39]
	v_mfma_f32_16x16x32_bf16 v[36:39], v[148:151], v[196:199], v[36:39]
	v_mfma_f32_16x16x32_bf16 v[68:71], v[144:147], v[184:187], v[68:71]
	v_mfma_f32_16x16x32_bf16 v[68:71], v[148:151], v[188:191], v[68:71]
	v_mfma_f32_16x16x32_bf16 v[96:99], v[144:147], v[176:179], v[96:99]
	v_mfma_f32_16x16x32_bf16 v[96:99], v[148:151], v[180:183], v[96:99]
	v_mfma_f32_16x16x32_bf16 v[112:115], v[144:147], v[168:171], v[112:115]
	v_mfma_f32_16x16x32_bf16 v[112:115], v[148:151], v[172:175], v[112:115]
	s_setprio 0
	s_setprio 1
	s_waitcnt lgkmcnt(0)
	v_mfma_f32_16x16x32_bf16 v[124:127], v[152:155], v[168:171], v[124:127]
	v_mfma_f32_16x16x32_bf16 v[124:127], v[156:159], v[172:175], v[124:127]
	v_mfma_f32_16x16x32_bf16 v[108:111], v[152:155], v[176:179], v[108:111]
	v_mfma_f32_16x16x32_bf16 v[108:111], v[156:159], v[180:183], v[108:111]
	v_mfma_f32_16x16x32_bf16 v[88:91], v[152:155], v[184:187], v[88:91]
	v_mfma_f32_16x16x32_bf16 v[88:91], v[156:159], v[188:191], v[88:91]
	v_mfma_f32_16x16x32_bf16 v[56:59], v[152:155], v[192:195], v[56:59]
	v_mfma_f32_16x16x32_bf16 v[56:59], v[156:159], v[196:199], v[56:59]
	v_mfma_f32_16x16x32_bf16 v[40:43], v[160:163], v[192:195], v[40:43]
	v_mfma_f32_16x16x32_bf16 v[40:43], v[164:167], v[196:199], v[40:43]
	v_mfma_f32_16x16x32_bf16 v[72:75], v[160:163], v[184:187], v[72:75]
	v_mfma_f32_16x16x32_bf16 v[72:75], v[164:167], v[188:191], v[72:75]
	v_mfma_f32_16x16x32_bf16 v[100:103], v[160:163], v[176:179], v[100:103]
	v_mfma_f32_16x16x32_bf16 v[100:103], v[164:167], v[180:183], v[100:103]
	v_mfma_f32_16x16x32_bf16 v[116:119], v[160:163], v[168:171], v[116:119]
	s_barrier
	v_mfma_f32_16x16x32_bf16 v[116:119], v[164:167], v[172:175], v[116:119]
	s_setprio 0
	s_add_u32 s88, s56, 0x2000
	ds_read_b128 v[168:171], v140 offset:16384
	ds_read_b128 v[172:175], v140 offset:17408
	ds_read_b128 v[176:179], v140 offset:18432
	ds_read_b128 v[180:183], v140 offset:19456
	ds_read_b128 v[184:187], v140 offset:20480
	ds_read_b128 v[188:191], v140 offset:21504
	ds_read_b128 v[192:195], v140 offset:22528
	ds_read_b128 v[196:199], v140 offset:23552
	s_mov_b32 m0, s41
	s_nop 0
	global_load_lds_dwordx4 v136, s[56:57]
	s_addc_u32 s89, s57, 0
	s_mov_b32 m0, s59
	s_nop 0
	global_load_lds_dwordx4 v136, s[88:89]
	s_add_u32 s88, s56, 0x4000
	s_addc_u32 s89, s57, 0
	s_mov_b32 m0, s60
	s_nop 0
	global_load_lds_dwordx4 v136, s[88:89]
	s_add_u32 s88, s56, 0x6000
	s_addc_u32 s89, s57, 0
	s_mov_b32 m0, s61
	s_nop 0
	global_load_lds_dwordx4 v136, s[88:89]
	s_add_u32 s88, s46, 0x2000
	s_mov_b32 m0, s58
	s_nop 0
	global_load_lds_dwordx4 v136, s[46:47]
	s_addc_u32 s89, s47, 0
	s_mov_b32 m0, s62
	s_nop 0
	global_load_lds_dwordx4 v136, s[88:89]
	s_waitcnt vmcnt(8)
	s_waitcnt lgkmcnt(0)
	s_barrier
	s_setprio 1
	s_waitcnt lgkmcnt(7)
	s_waitcnt lgkmcnt(0)
	v_mfma_f32_16x16x32_bf16 v[92:95], v[128:131], v[168:171], v[92:95]
	v_mfma_f32_16x16x32_bf16 v[92:95], v[132:135], v[172:175], v[92:95]
	v_mfma_f32_16x16x32_bf16 v[60:63], v[128:131], v[176:179], v[60:63]
	v_mfma_f32_16x16x32_bf16 v[60:63], v[132:135], v[180:183], v[60:63]
	v_mfma_f32_16x16x32_bf16 v[28:31], v[128:131], v[184:187], v[28:31]
	v_mfma_f32_16x16x32_bf16 v[28:31], v[132:135], v[188:191], v[28:31]
	v_mfma_f32_16x16x32_bf16 v[12:15], v[128:131], v[192:195], v[12:15]
	v_mfma_f32_16x16x32_bf16 v[12:15], v[132:135], v[196:199], v[12:15]
	v_mfma_f32_16x16x32_bf16 v[8:11], v[144:147], v[192:195], v[8:11]
	v_mfma_f32_16x16x32_bf16 v[8:11], v[148:151], v[196:199], v[8:11]
	v_mfma_f32_16x16x32_bf16 v[24:27], v[144:147], v[184:187], v[24:27]
	v_mfma_f32_16x16x32_bf16 v[24:27], v[148:151], v[188:191], v[24:27]
	v_mfma_f32_16x16x32_bf16 v[48:51], v[144:147], v[176:179], v[48:51]
	v_mfma_f32_16x16x32_bf16 v[48:51], v[148:151], v[180:183], v[48:51]
	v_mfma_f32_16x16x32_bf16 v[80:83], v[144:147], v[168:171], v[80:83]
	v_mfma_f32_16x16x32_bf16 v[80:83], v[148:151], v[172:175], v[80:83]
	s_setprio 0
	s_setprio 1
	s_waitcnt lgkmcnt(0)
	v_mfma_f32_16x16x32_bf16 v[76:79], v[152:155], v[168:171], v[76:79]
	v_mfma_f32_16x16x32_bf16 v[76:79], v[156:159], v[172:175], v[76:79]
	v_mfma_f32_16x16x32_bf16 v[44:47], v[152:155], v[176:179], v[44:47]
	v_mfma_f32_16x16x32_bf16 v[44:47], v[156:159], v[180:183], v[44:47]
	v_mfma_f32_16x16x32_bf16 v[20:23], v[152:155], v[184:187], v[20:23]
	v_mfma_f32_16x16x32_bf16 v[20:23], v[156:159], v[188:191], v[20:23]
	v_mfma_f32_16x16x32_bf16 v[4:7], v[152:155], v[192:195], v[4:7]
	v_mfma_f32_16x16x32_bf16 v[4:7], v[156:159], v[196:199], v[4:7]
	v_mfma_f32_16x16x32_bf16 v[0:3], v[160:163], v[192:195], v[0:3]
	v_mfma_f32_16x16x32_bf16 v[0:3], v[164:167], v[196:199], v[0:3]
	v_mfma_f32_16x16x32_bf16 v[16:19], v[160:163], v[184:187], v[16:19]
	v_mfma_f32_16x16x32_bf16 v[16:19], v[164:167], v[188:191], v[16:19]
	v_mfma_f32_16x16x32_bf16 v[32:35], v[160:163], v[176:179], v[32:35]
	v_mfma_f32_16x16x32_bf16 v[32:35], v[164:167], v[180:183], v[32:35]
	v_mfma_f32_16x16x32_bf16 v[64:67], v[160:163], v[168:171], v[64:67]
	s_barrier
	v_mfma_f32_16x16x32_bf16 v[64:67], v[164:167], v[172:175], v[64:67]
	s_setprio 0
	ds_read_b128 v[128:131], v141
	ds_read_b128 v[132:135], v141 offset:1024
	ds_read_b128 v[144:147], v141 offset:2048
	ds_read_b128 v[148:151], v141 offset:3072
	ds_read_b128 v[152:155], v142
	ds_read_b128 v[156:159], v142 offset:1024
	ds_read_b128 v[160:163], v142 offset:2048
	ds_read_b128 v[164:167], v142 offset:3072
	ds_read_b128 v[168:171], v140 offset:32768
	ds_read_b128 v[172:175], v140 offset:33792
	ds_read_b128 v[176:179], v140 offset:34816
	ds_read_b128 v[180:183], v140 offset:35840
	ds_read_b128 v[184:187], v140 offset:36864
	ds_read_b128 v[188:191], v140 offset:37888
	ds_read_b128 v[192:195], v140 offset:38912
	ds_read_b128 v[196:199], v140 offset:39936
	s_add_u32 s88, s46, 0x4000
	s_addc_u32 s89, s47, 0
	s_mov_b32 m0, s63
	s_nop 0
	global_load_lds_dwordx4 v136, s[88:89]
	s_add_u32 s88, s46, 0x6000
	s_addc_u32 s89, s47, 0
	s_mov_b32 m0, s64
	s_nop 0
	global_load_lds_dwordx4 v136, s[88:89]
	s_waitcnt vmcnt(8)
	s_waitcnt lgkmcnt(0)
	s_barrier
	s_setprio 1
	s_waitcnt lgkmcnt(7)
	s_waitcnt lgkmcnt(0)
	v_mfma_f32_16x16x32_bf16 v[120:123], v[128:131], v[168:171], v[120:123]
	v_mfma_f32_16x16x32_bf16 v[120:123], v[132:135], v[172:175], v[120:123]
	v_mfma_f32_16x16x32_bf16 v[104:107], v[128:131], v[176:179], v[104:107]
	v_mfma_f32_16x16x32_bf16 v[104:107], v[132:135], v[180:183], v[104:107]
	v_mfma_f32_16x16x32_bf16 v[84:87], v[128:131], v[184:187], v[84:87]
	v_mfma_f32_16x16x32_bf16 v[84:87], v[132:135], v[188:191], v[84:87]
	v_mfma_f32_16x16x32_bf16 v[52:55], v[128:131], v[192:195], v[52:55]
	v_mfma_f32_16x16x32_bf16 v[52:55], v[132:135], v[196:199], v[52:55]
	v_mfma_f32_16x16x32_bf16 v[36:39], v[144:147], v[192:195], v[36:39]
	v_mfma_f32_16x16x32_bf16 v[36:39], v[148:151], v[196:199], v[36:39]
	v_mfma_f32_16x16x32_bf16 v[68:71], v[144:147], v[184:187], v[68:71]
	v_mfma_f32_16x16x32_bf16 v[68:71], v[148:151], v[188:191], v[68:71]
	v_mfma_f32_16x16x32_bf16 v[96:99], v[144:147], v[176:179], v[96:99]
	v_mfma_f32_16x16x32_bf16 v[96:99], v[148:151], v[180:183], v[96:99]
	v_mfma_f32_16x16x32_bf16 v[112:115], v[144:147], v[168:171], v[112:115]
	v_mfma_f32_16x16x32_bf16 v[112:115], v[148:151], v[172:175], v[112:115]
	s_setprio 0
	s_setprio 1
	s_waitcnt lgkmcnt(0)
	v_mfma_f32_16x16x32_bf16 v[124:127], v[152:155], v[168:171], v[124:127]
	v_mfma_f32_16x16x32_bf16 v[124:127], v[156:159], v[172:175], v[124:127]
	v_mfma_f32_16x16x32_bf16 v[108:111], v[152:155], v[176:179], v[108:111]
	v_mfma_f32_16x16x32_bf16 v[108:111], v[156:159], v[180:183], v[108:111]
	v_mfma_f32_16x16x32_bf16 v[88:91], v[152:155], v[184:187], v[88:91]
	v_mfma_f32_16x16x32_bf16 v[88:91], v[156:159], v[188:191], v[88:91]
	v_mfma_f32_16x16x32_bf16 v[56:59], v[152:155], v[192:195], v[56:59]
	v_mfma_f32_16x16x32_bf16 v[56:59], v[156:159], v[196:199], v[56:59]
	v_mfma_f32_16x16x32_bf16 v[40:43], v[160:163], v[192:195], v[40:43]
	v_mfma_f32_16x16x32_bf16 v[40:43], v[164:167], v[196:199], v[40:43]
	v_mfma_f32_16x16x32_bf16 v[72:75], v[160:163], v[184:187], v[72:75]
	v_mfma_f32_16x16x32_bf16 v[72:75], v[164:167], v[188:191], v[72:75]
	v_mfma_f32_16x16x32_bf16 v[100:103], v[160:163], v[176:179], v[100:103]
	v_mfma_f32_16x16x32_bf16 v[100:103], v[164:167], v[180:183], v[100:103]
	v_mfma_f32_16x16x32_bf16 v[116:119], v[160:163], v[168:171], v[116:119]
	s_barrier
	v_mfma_f32_16x16x32_bf16 v[116:119], v[164:167], v[172:175], v[116:119]
	s_setprio 0
	ds_read_b128 v[168:171], v140 offset:49152
	ds_read_b128 v[172:175], v140 offset:50176
	ds_read_b128 v[176:179], v140 offset:51200
	ds_read_b128 v[180:183], v140 offset:52224
	ds_read_b128 v[184:187], v140 offset:53248
	ds_read_b128 v[188:191], v140 offset:54272
	ds_read_b128 v[192:195], v140 offset:55296
	ds_read_b128 v[196:199], v140 offset:56320
	s_mov_b32 m0, s68
	s_nop 0
	global_load_lds_dwordx4 v136, s[52:53]
	s_add_u32 s52, s56, 0xa000
	s_addc_u32 s53, s57, 0
	s_mov_b32 m0, s69
	s_nop 0
	global_load_lds_dwordx4 v136, s[52:53]
	s_add_u32 s52, s56, 0xc000
	s_addc_u32 s53, s57, 0
	s_mov_b32 m0, s72
	s_nop 0
	global_load_lds_dwordx4 v136, s[52:53]
	s_add_u32 s52, s56, 0xe000
	s_addc_u32 s53, s57, 0
	s_mov_b32 m0, s73
	s_nop 0
	global_load_lds_dwordx4 v136, s[52:53]
	s_add_u32 s46, s46, 0xa000
	s_mov_b32 m0, s70
	s_nop 0
	global_load_lds_dwordx4 v136, s[48:49]
	s_addc_u32 s47, s47, 0
	s_mov_b32 m0, s71
	s_nop 0
	global_load_lds_dwordx4 v136, s[46:47]
	s_waitcnt vmcnt(8)
	s_waitcnt lgkmcnt(0)
	s_barrier
	s_setprio 1
	s_waitcnt lgkmcnt(7)
	s_waitcnt lgkmcnt(0)
	v_mfma_f32_16x16x32_bf16 v[92:95], v[128:131], v[168:171], v[92:95]
	v_mfma_f32_16x16x32_bf16 v[92:95], v[132:135], v[172:175], v[92:95]
	v_mfma_f32_16x16x32_bf16 v[60:63], v[128:131], v[176:179], v[60:63]
	v_mfma_f32_16x16x32_bf16 v[60:63], v[132:135], v[180:183], v[60:63]
	v_mfma_f32_16x16x32_bf16 v[28:31], v[128:131], v[184:187], v[28:31]
	v_mfma_f32_16x16x32_bf16 v[28:31], v[132:135], v[188:191], v[28:31]
	v_mfma_f32_16x16x32_bf16 v[12:15], v[128:131], v[192:195], v[12:15]
	v_mfma_f32_16x16x32_bf16 v[12:15], v[132:135], v[196:199], v[12:15]
	v_mfma_f32_16x16x32_bf16 v[8:11], v[144:147], v[192:195], v[8:11]
	v_mfma_f32_16x16x32_bf16 v[8:11], v[148:151], v[196:199], v[8:11]
	v_mfma_f32_16x16x32_bf16 v[24:27], v[144:147], v[184:187], v[24:27]
	v_mfma_f32_16x16x32_bf16 v[24:27], v[148:151], v[188:191], v[24:27]
	v_mfma_f32_16x16x32_bf16 v[48:51], v[144:147], v[176:179], v[48:51]
	v_mfma_f32_16x16x32_bf16 v[48:51], v[148:151], v[180:183], v[48:51]
	v_mfma_f32_16x16x32_bf16 v[80:83], v[144:147], v[168:171], v[80:83]
	v_mfma_f32_16x16x32_bf16 v[80:83], v[148:151], v[172:175], v[80:83]
	s_setprio 0
	s_setprio 1
	s_waitcnt lgkmcnt(0)
	v_mfma_f32_16x16x32_bf16 v[76:79], v[152:155], v[168:171], v[76:79]
	v_mfma_f32_16x16x32_bf16 v[76:79], v[156:159], v[172:175], v[76:79]
	v_mfma_f32_16x16x32_bf16 v[44:47], v[152:155], v[176:179], v[44:47]
	v_mfma_f32_16x16x32_bf16 v[44:47], v[156:159], v[180:183], v[44:47]
	v_mfma_f32_16x16x32_bf16 v[20:23], v[152:155], v[184:187], v[20:23]
	v_mfma_f32_16x16x32_bf16 v[20:23], v[156:159], v[188:191], v[20:23]
	v_mfma_f32_16x16x32_bf16 v[4:7], v[152:155], v[192:195], v[4:7]
	v_mfma_f32_16x16x32_bf16 v[4:7], v[156:159], v[196:199], v[4:7]
	v_mfma_f32_16x16x32_bf16 v[0:3], v[160:163], v[192:195], v[0:3]
	v_mfma_f32_16x16x32_bf16 v[0:3], v[164:167], v[196:199], v[0:3]
	v_mfma_f32_16x16x32_bf16 v[16:19], v[160:163], v[184:187], v[16:19]
	v_mfma_f32_16x16x32_bf16 v[16:19], v[164:167], v[188:191], v[16:19]
	v_mfma_f32_16x16x32_bf16 v[32:35], v[160:163], v[176:179], v[32:35]
	v_mfma_f32_16x16x32_bf16 v[32:35], v[164:167], v[180:183], v[32:35]
	v_mfma_f32_16x16x32_bf16 v[64:67], v[160:163], v[168:171], v[64:67]
	s_barrier
	v_mfma_f32_16x16x32_bf16 v[64:67], v[164:167], v[172:175], v[64:67]
	s_setprio 0
	s_add_i32 s83, s83, 2
	s_add_u32 s81, s81, 0x10000
	s_addc_u32 s82, s82, 0
	s_cmp_gt_u32 s83, 61
	s_mov_b64 s[52:53], s[2:3]
	s_cbranch_scc0 .LBB0_1539
	s_nop 7
	s_and_b64 vcc, exec, s[8:9]
	s_cbranch_vccz .LBB0_1542
	s_barrier

.LBB0_1953:
	ds_read_b128 v[134:137], v128
	ds_read_b128 v[138:141], v128 offset:1024
	ds_read_b128 v[142:145], v128 offset:2048
	ds_read_b128 v[146:149], v128 offset:3072
	ds_read_b128 v[150:153], v129
	ds_read_b128 v[154:157], v129 offset:1024
	ds_read_b128 v[158:161], v129 offset:2048
	ds_read_b128 v[162:165], v129 offset:3072
	s_add_u32 s2, s28, 0x10000
	s_addc_u32 s3, s29, 0
	s_cmp_eq_u32 s77, 8
	s_cselect_b32 s38, s26, s2
	s_cselect_b32 s39, s27, s3
	s_cselect_b32 s42, s23, s75
	s_cselect_b32 s43, s25, s76
	s_add_u32 s40, s38, 0x8000
	s_addc_u32 s41, s39, 0
	ds_read_b128 v[166:169], v130
	ds_read_b128 v[170:173], v130 offset:1024
	ds_read_b128 v[174:177], v130 offset:2048
	ds_read_b128 v[178:181], v130 offset:3072
	ds_read_b128 v[182:185], v130 offset:4096
	ds_read_b128 v[192:195], v130 offset:5120
	ds_read_b128 v[196:199], v130 offset:6144
	ds_read_b128 v[200:203], v130 offset:7168
	s_add_u32 s78, s28, 0xc000
	s_addc_u32 s79, s29, 0
	s_mov_b32 m0, s63
	s_nop 0
	global_load_lds_dwordx4 v210, s[78:79]
	s_add_u32 s28, s28, 0xe000
	s_addc_u32 s29, s29, 0
	s_mov_b32 m0, s66
	s_nop 0
	global_load_lds_dwordx4 v210, s[28:29]
	s_waitcnt vmcnt(8)
	s_waitcnt lgkmcnt(0)
	s_barrier
	s_setprio 1
	s_waitcnt lgkmcnt(7)
	s_waitcnt lgkmcnt(0)
	v_mfma_f32_16x16x32_bf16 v[124:127], v[134:137], v[166:169], v[124:127]
	v_mfma_f32_16x16x32_bf16 v[124:127], v[138:141], v[170:173], v[124:127]
	v_mfma_f32_16x16x32_bf16 v[108:111], v[134:137], v[174:177], v[108:111]
	v_mfma_f32_16x16x32_bf16 v[108:111], v[138:141], v[178:181], v[108:111]
	v_mfma_f32_16x16x32_bf16 v[92:95], v[134:137], v[182:185], v[92:95]
	v_mfma_f32_16x16x32_bf16 v[92:95], v[138:141], v[192:195], v[92:95]
	v_mfma_f32_16x16x32_bf16 v[76:79], v[134:137], v[196:199], v[76:79]
	v_mfma_f32_16x16x32_bf16 v[76:79], v[138:141], v[200:203], v[76:79]
	v_mfma_f32_16x16x32_bf16 v[72:75], v[142:145], v[196:199], v[72:75]
	v_mfma_f32_16x16x32_bf16 v[72:75], v[146:149], v[200:203], v[72:75]
	v_mfma_f32_16x16x32_bf16 v[88:91], v[142:145], v[182:185], v[88:91]
	v_mfma_f32_16x16x32_bf16 v[88:91], v[146:149], v[192:195], v[88:91]
	v_mfma_f32_16x16x32_bf16 v[104:107], v[142:145], v[174:177], v[104:107]
	v_mfma_f32_16x16x32_bf16 v[104:107], v[146:149], v[178:181], v[104:107]
	v_mfma_f32_16x16x32_bf16 v[120:123], v[142:145], v[166:169], v[120:123]
	v_mfma_f32_16x16x32_bf16 v[120:123], v[146:149], v[170:173], v[120:123]
	s_setprio 0
	s_setprio 1
	s_waitcnt lgkmcnt(0)
	v_mfma_f32_16x16x32_bf16 v[116:119], v[150:153], v[166:169], v[116:119]
	v_mfma_f32_16x16x32_bf16 v[116:119], v[154:157], v[170:173], v[116:119]
	v_mfma_f32_16x16x32_bf16 v[100:103], v[150:153], v[174:177], v[100:103]
	v_mfma_f32_16x16x32_bf16 v[100:103], v[154:157], v[178:181], v[100:103]
	v_mfma_f32_16x16x32_bf16 v[84:87], v[150:153], v[182:185], v[84:87]
	v_mfma_f32_16x16x32_bf16 v[84:87], v[154:157], v[192:195], v[84:87]
	v_mfma_f32_16x16x32_bf16 v[68:71], v[150:153], v[196:199], v[68:71]
	v_mfma_f32_16x16x32_bf16 v[68:71], v[154:157], v[200:203], v[68:71]
	v_mfma_f32_16x16x32_bf16 v[64:67], v[158:161], v[196:199], v[64:67]
	v_mfma_f32_16x16x32_bf16 v[64:67], v[162:165], v[200:203], v[64:67]
	v_mfma_f32_16x16x32_bf16 v[80:83], v[158:161], v[182:185], v[80:83]
	v_mfma_f32_16x16x32_bf16 v[80:83], v[162:165], v[192:195], v[80:83]
	v_mfma_f32_16x16x32_bf16 v[96:99], v[158:161], v[174:177], v[96:99]
	v_mfma_f32_16x16x32_bf16 v[96:99], v[162:165], v[178:181], v[96:99]
	v_mfma_f32_16x16x32_bf16 v[112:115], v[158:161], v[166:169], v[112:115]
	s_barrier
	v_mfma_f32_16x16x32_bf16 v[112:115], v[162:165], v[170:173], v[112:115]
	s_setprio 0
	s_add_u32 s28, s42, 0x2000
	ds_read_b128 v[166:169], v130 offset:16384
	ds_read_b128 v[170:173], v130 offset:17408
	ds_read_b128 v[174:177], v130 offset:18432
	ds_read_b128 v[178:181], v130 offset:19456
	ds_read_b128 v[182:185], v130 offset:20480
	ds_read_b128 v[192:195], v130 offset:21504
	ds_read_b128 v[196:199], v130 offset:22528
	ds_read_b128 v[200:203], v130 offset:23552
	s_mov_b32 m0, s46
	s_nop 0
	global_load_lds_dwordx4 v210, s[42:43]
	s_addc_u32 s29, s43, 0
	s_mov_b32 m0, s47
	s_nop 0
	global_load_lds_dwordx4 v210, s[28:29]
	s_add_u32 s28, s42, 0x4000
	s_addc_u32 s29, s43, 0
	s_mov_b32 m0, s48
	s_nop 0
	global_load_lds_dwordx4 v210, s[28:29]
	s_add_u32 s28, s42, 0x6000
	s_addc_u32 s29, s43, 0
	s_mov_b32 m0, s49
	s_nop 0
	global_load_lds_dwordx4 v210, s[28:29]
	s_add_u32 s28, s38, 0x2000
	s_mov_b32 m0, s45
	s_nop 0
	global_load_lds_dwordx4 v210, s[38:39]
	s_addc_u32 s29, s39, 0
	s_mov_b32 m0, s50
	s_nop 0
	global_load_lds_dwordx4 v210, s[28:29]
	s_waitcnt vmcnt(8)
	s_waitcnt lgkmcnt(0)
	s_barrier
	s_setprio 1
	s_waitcnt lgkmcnt(7)
	s_waitcnt lgkmcnt(0)
	v_mfma_f32_16x16x32_bf16 v[60:63], v[134:137], v[166:169], v[60:63]
	v_mfma_f32_16x16x32_bf16 v[60:63], v[138:141], v[170:173], v[60:63]
	v_mfma_f32_16x16x32_bf16 v[44:47], v[134:137], v[174:177], v[44:47]
	v_mfma_f32_16x16x32_bf16 v[44:47], v[138:141], v[178:181], v[44:47]
	v_mfma_f32_16x16x32_bf16 v[28:31], v[134:137], v[182:185], v[28:31]
	v_mfma_f32_16x16x32_bf16 v[28:31], v[138:141], v[192:195], v[28:31]
	v_mfma_f32_16x16x32_bf16 v[12:15], v[134:137], v[196:199], v[12:15]
	v_mfma_f32_16x16x32_bf16 v[12:15], v[138:141], v[200:203], v[12:15]
	v_mfma_f32_16x16x32_bf16 v[8:11], v[142:145], v[196:199], v[8:11]
	v_mfma_f32_16x16x32_bf16 v[8:11], v[146:149], v[200:203], v[8:11]
	v_mfma_f32_16x16x32_bf16 v[24:27], v[142:145], v[182:185], v[24:27]
	v_mfma_f32_16x16x32_bf16 v[24:27], v[146:149], v[192:195], v[24:27]
	v_mfma_f32_16x16x32_bf16 v[40:43], v[142:145], v[174:177], v[40:43]
	v_mfma_f32_16x16x32_bf16 v[40:43], v[146:149], v[178:181], v[40:43]
	v_mfma_f32_16x16x32_bf16 v[56:59], v[142:145], v[166:169], v[56:59]
	v_mfma_f32_16x16x32_bf16 v[56:59], v[146:149], v[170:173], v[56:59]
	s_setprio 0
	s_setprio 1
	s_waitcnt lgkmcnt(0)
	v_mfma_f32_16x16x32_bf16 v[52:55], v[150:153], v[166:169], v[52:55]
	v_mfma_f32_16x16x32_bf16 v[52:55], v[154:157], v[170:173], v[52:55]
	v_mfma_f32_16x16x32_bf16 v[36:39], v[150:153], v[174:177], v[36:39]
	v_mfma_f32_16x16x32_bf16 v[36:39], v[154:157], v[178:181], v[36:39]
	v_mfma_f32_16x16x32_bf16 v[20:23], v[150:153], v[182:185], v[20:23]
	v_mfma_f32_16x16x32_bf16 v[20:23], v[154:157], v[192:195], v[20:23]
	v_mfma_f32_16x16x32_bf16 v[4:7], v[150:153], v[196:199], v[4:7]
	v_mfma_f32_16x16x32_bf16 v[4:7], v[154:157], v[200:203], v[4:7]
	v_mfma_f32_16x16x32_bf16 v[0:3], v[158:161], v[196:199], v[0:3]
	v_mfma_f32_16x16x32_bf16 v[0:3], v[162:165], v[200:203], v[0:3]
	v_mfma_f32_16x16x32_bf16 v[16:19], v[158:161], v[182:185], v[16:19]
	v_mfma_f32_16x16x32_bf16 v[16:19], v[162:165], v[192:195], v[16:19]
	v_mfma_f32_16x16x32_bf16 v[32:35], v[158:161], v[174:177], v[32:35]
	v_mfma_f32_16x16x32_bf16 v[32:35], v[162:165], v[178:181], v[32:35]
	v_mfma_f32_16x16x32_bf16 v[48:51], v[158:161], v[166:169], v[48:51]
	s_barrier
	v_mfma_f32_16x16x32_bf16 v[48:51], v[162:165], v[170:173], v[48:51]
	s_setprio 0
	ds_read_b128 v[134:137], v131
	ds_read_b128 v[138:141], v131 offset:1024
	ds_read_b128 v[142:145], v131 offset:2048
	ds_read_b128 v[146:149], v131 offset:3072
	ds_read_b128 v[150:153], v132
	ds_read_b128 v[154:157], v132 offset:1024
	ds_read_b128 v[158:161], v132 offset:2048
	ds_read_b128 v[162:165], v132 offset:3072
	ds_read_b128 v[166:169], v130 offset:32768
	ds_read_b128 v[170:173], v130 offset:33792
	ds_read_b128 v[174:177], v130 offset:34816
	ds_read_b128 v[178:181], v130 offset:35840
	ds_read_b128 v[182:185], v130 offset:36864
	ds_read_b128 v[192:195], v130 offset:37888
	ds_read_b128 v[196:199], v130 offset:38912
	ds_read_b128 v[200:203], v130 offset:39936
	s_add_u32 s28, s38, 0x4000
	s_addc_u32 s29, s39, 0
	s_mov_b32 m0, s51
	s_nop 0
	global_load_lds_dwordx4 v210, s[28:29]
	s_add_u32 s28, s38, 0x6000
	s_addc_u32 s29, s39, 0
	s_mov_b32 m0, s52
	s_nop 0
	global_load_lds_dwordx4 v210, s[28:29]
	s_waitcnt vmcnt(8)
	s_waitcnt lgkmcnt(0)
	s_barrier
	s_setprio 1
	s_waitcnt lgkmcnt(7)
	s_waitcnt lgkmcnt(0)
	v_mfma_f32_16x16x32_bf16 v[124:127], v[134:137], v[166:169], v[124:127]
	v_mfma_f32_16x16x32_bf16 v[124:127], v[138:141], v[170:173], v[124:127]
	v_mfma_f32_16x16x32_bf16 v[108:111], v[134:137], v[174:177], v[108:111]
	v_mfma_f32_16x16x32_bf16 v[108:111], v[138:141], v[178:181], v[108:111]
	v_mfma_f32_16x16x32_bf16 v[92:95], v[134:137], v[182:185], v[92:95]
	v_mfma_f32_16x16x32_bf16 v[92:95], v[138:141], v[192:195], v[92:95]
	v_mfma_f32_16x16x32_bf16 v[76:79], v[134:137], v[196:199], v[76:79]
	v_mfma_f32_16x16x32_bf16 v[76:79], v[138:141], v[200:203], v[76:79]
	v_mfma_f32_16x16x32_bf16 v[72:75], v[142:145], v[196:199], v[72:75]
	v_mfma_f32_16x16x32_bf16 v[72:75], v[146:149], v[200:203], v[72:75]
	v_mfma_f32_16x16x32_bf16 v[88:91], v[142:145], v[182:185], v[88:91]
	v_mfma_f32_16x16x32_bf16 v[88:91], v[146:149], v[192:195], v[88:91]
	v_mfma_f32_16x16x32_bf16 v[104:107], v[142:145], v[174:177], v[104:107]
	v_mfma_f32_16x16x32_bf16 v[104:107], v[146:149], v[178:181], v[104:107]
	v_mfma_f32_16x16x32_bf16 v[120:123], v[142:145], v[166:169], v[120:123]
	v_mfma_f32_16x16x32_bf16 v[120:123], v[146:149], v[170:173], v[120:123]
	s_setprio 0
	s_setprio 1
	s_waitcnt lgkmcnt(0)
	v_mfma_f32_16x16x32_bf16 v[116:119], v[150:153], v[166:169], v[116:119]
	v_mfma_f32_16x16x32_bf16 v[116:119], v[154:157], v[170:173], v[116:119]
	v_mfma_f32_16x16x32_bf16 v[100:103], v[150:153], v[174:177], v[100:103]
	v_mfma_f32_16x16x32_bf16 v[100:103], v[154:157], v[178:181], v[100:103]
	v_mfma_f32_16x16x32_bf16 v[84:87], v[150:153], v[182:185], v[84:87]
	v_mfma_f32_16x16x32_bf16 v[84:87], v[154:157], v[192:195], v[84:87]
	v_mfma_f32_16x16x32_bf16 v[68:71], v[150:153], v[196:199], v[68:71]
	v_mfma_f32_16x16x32_bf16 v[68:71], v[154:157], v[200:203], v[68:71]
	v_mfma_f32_16x16x32_bf16 v[64:67], v[158:161], v[196:199], v[64:67]
	v_mfma_f32_16x16x32_bf16 v[64:67], v[162:165], v[200:203], v[64:67]
	v_mfma_f32_16x16x32_bf16 v[80:83], v[158:161], v[182:185], v[80:83]
	v_mfma_f32_16x16x32_bf16 v[80:83], v[162:165], v[192:195], v[80:83]
	v_mfma_f32_16x16x32_bf16 v[96:99], v[158:161], v[174:177], v[96:99]
	v_mfma_f32_16x16x32_bf16 v[96:99], v[162:165], v[178:181], v[96:99]
	v_mfma_f32_16x16x32_bf16 v[112:115], v[158:161], v[166:169], v[112:115]
	s_barrier
	v_mfma_f32_16x16x32_bf16 v[112:115], v[162:165], v[170:173], v[112:115]
	s_setprio 0
	s_add_u32 s28, s42, 0x8000
	s_addc_u32 s29, s43, 0
	ds_read_b128 v[166:169], v130 offset:49152
	ds_read_b128 v[170:173], v130 offset:50176
	ds_read_b128 v[174:177], v130 offset:51200
	ds_read_b128 v[178:181], v130 offset:52224
	ds_read_b128 v[182:185], v130 offset:53248
	ds_read_b128 v[192:195], v130 offset:54272
	ds_read_b128 v[196:199], v130 offset:55296
	ds_read_b128 v[200:203], v130 offset:56320
	s_mov_b32 m0, s53
	s_nop 0
	global_load_lds_dwordx4 v210, s[28:29]
	s_add_u32 s28, s42, 0xa000
	s_addc_u32 s29, s43, 0
	s_mov_b32 m0, s54
	s_nop 0
	global_load_lds_dwordx4 v210, s[28:29]
	s_add_u32 s28, s42, 0xc000
	s_addc_u32 s29, s43, 0
	s_mov_b32 m0, s57
	s_nop 0
	global_load_lds_dwordx4 v210, s[28:29]
	s_add_u32 s28, s42, 0xe000
	s_addc_u32 s29, s43, 0
	s_mov_b32 m0, s58
	s_nop 0
	global_load_lds_dwordx4 v210, s[28:29]
	s_add_u32 s28, s38, 0xa000
	s_mov_b32 m0, s55
	s_nop 0
	global_load_lds_dwordx4 v210, s[40:41]
	s_addc_u32 s29, s39, 0
	s_mov_b32 m0, s56
	s_nop 0
	global_load_lds_dwordx4 v210, s[28:29]
	s_waitcnt vmcnt(8)
	s_waitcnt lgkmcnt(0)
	s_barrier
	s_setprio 1
	s_waitcnt lgkmcnt(7)
	s_waitcnt lgkmcnt(0)
	v_mfma_f32_16x16x32_bf16 v[60:63], v[134:137], v[166:169], v[60:63]
	v_mfma_f32_16x16x32_bf16 v[60:63], v[138:141], v[170:173], v[60:63]
	v_mfma_f32_16x16x32_bf16 v[44:47], v[134:137], v[174:177], v[44:47]
	v_mfma_f32_16x16x32_bf16 v[44:47], v[138:141], v[178:181], v[44:47]
	v_mfma_f32_16x16x32_bf16 v[28:31], v[134:137], v[182:185], v[28:31]
	v_mfma_f32_16x16x32_bf16 v[28:31], v[138:141], v[192:195], v[28:31]
	v_mfma_f32_16x16x32_bf16 v[12:15], v[134:137], v[196:199], v[12:15]
	v_mfma_f32_16x16x32_bf16 v[12:15], v[138:141], v[200:203], v[12:15]
	v_mfma_f32_16x16x32_bf16 v[8:11], v[142:145], v[196:199], v[8:11]
	v_mfma_f32_16x16x32_bf16 v[8:11], v[146:149], v[200:203], v[8:11]
	v_mfma_f32_16x16x32_bf16 v[24:27], v[142:145], v[182:185], v[24:27]
	v_mfma_f32_16x16x32_bf16 v[24:27], v[146:149], v[192:195], v[24:27]
	v_mfma_f32_16x16x32_bf16 v[40:43], v[142:145], v[174:177], v[40:43]
	v_mfma_f32_16x16x32_bf16 v[40:43], v[146:149], v[178:181], v[40:43]
	v_mfma_f32_16x16x32_bf16 v[56:59], v[142:145], v[166:169], v[56:59]
	v_mfma_f32_16x16x32_bf16 v[56:59], v[146:149], v[170:173], v[56:59]
	s_setprio 0
	s_setprio 1
	s_waitcnt lgkmcnt(0)
	v_mfma_f32_16x16x32_bf16 v[52:55], v[150:153], v[166:169], v[52:55]
	v_mfma_f32_16x16x32_bf16 v[52:55], v[154:157], v[170:173], v[52:55]
	v_mfma_f32_16x16x32_bf16 v[36:39], v[150:153], v[174:177], v[36:39]
	v_mfma_f32_16x16x32_bf16 v[36:39], v[154:157], v[178:181], v[36:39]
	v_mfma_f32_16x16x32_bf16 v[20:23], v[150:153], v[182:185], v[20:23]
	v_mfma_f32_16x16x32_bf16 v[20:23], v[154:157], v[192:195], v[20:23]
	v_mfma_f32_16x16x32_bf16 v[4:7], v[150:153], v[196:199], v[4:7]
	v_mfma_f32_16x16x32_bf16 v[4:7], v[154:157], v[200:203], v[4:7]
	v_mfma_f32_16x16x32_bf16 v[0:3], v[158:161], v[196:199], v[0:3]
	v_mfma_f32_16x16x32_bf16 v[0:3], v[162:165], v[200:203], v[0:3]
	v_mfma_f32_16x16x32_bf16 v[16:19], v[158:161], v[182:185], v[16:19]
	v_mfma_f32_16x16x32_bf16 v[16:19], v[162:165], v[192:195], v[16:19]
	v_mfma_f32_16x16x32_bf16 v[32:35], v[158:161], v[174:177], v[32:35]
	v_mfma_f32_16x16x32_bf16 v[32:35], v[162:165], v[178:181], v[32:35]
	v_mfma_f32_16x16x32_bf16 v[48:51], v[158:161], v[166:169], v[48:51]
	s_barrier
	v_mfma_f32_16x16x32_bf16 v[48:51], v[162:165], v[170:173], v[48:51]
	s_setprio 0
	s_add_i32 s77, s77, 2
	s_add_u32 s75, s75, 0x10000
	s_addc_u32 s76, s76, 0
	s_cmp_gt_u32 s77, 9
	s_mov_b64 s[28:29], s[2:3]
	s_cbranch_scc0 .LBB0_1953
	s_nop 7
	v_mbcnt_lo_u32_b32 v128, -1, 0
	v_mbcnt_hi_u32_b32 v128, -1, v128
	s_add_u32 s19, s69, s19
	v_lshlrev_b32_e32 v128, 4, v128
	v_add_u32_e32 v129, s60, v128
	v_add_u32_e32 v128, s62, v128
	s_addc_u32 s17, s70, s17
	s_mov_b32 s23, -2
	v_add_u32_e32 v128, 0, v128
	v_add_u32_e32 v129, 0, v129
